# GEMM MFMA order G6: same-accumulator pairs back to back (alternating k order), m-major snake over the 32-MFMA segment so every adjacent MFMA shares accumulator or an operand register; diff-attention p
# speedup vs baseline: 1.0219x; 1.0219x over previous
.LBB0_200:
	ds_read_b128 v[148:151], v169
	ds_read_b128 v[152:155], v169 offset:1024
	ds_read_b128 v[156:159], v169 offset:2048
	ds_read_b128 v[160:163], v169 offset:3072
	ds_read_b128 v[174:177], v170
	ds_read_b128 v[178:181], v170 offset:1024
	ds_read_b128 v[182:185], v170 offset:2048
	ds_read_b128 v[186:189], v170 offset:3072
	s_add_u32 s26, s6, 0xfff00800
	s_addc_u32 s27, s7, -1
	s_cmp_eq_u32 s34, 60
	s_cselect_b32 s29, s17, s27
	s_cselect_b32 s28, s23, s26
	s_cselect_b32 s27, s15, s31
	s_cselect_b32 s26, s25, s30
	v_lshl_add_u64 v[190:191], s[6:7], 0, v[138:139]
	s_add_i32 m0, s41, 0xc000
	s_nop 0
	global_load_lds_dwordx4 v[190:191], off
	v_lshl_add_u64 v[190:191], s[6:7], 0, v[140:141]
	s_add_i32 m0, s41, 0xe000
	s_nop 0
	global_load_lds_dwordx4 v[190:191], off
	ds_read_b128 v[190:193], v171
	ds_read_b128 v[194:197], v171 offset:1024
	ds_read_b128 v[198:201], v171 offset:2048
	ds_read_b128 v[202:205], v171 offset:3072
	ds_read_b128 v[206:209], v171 offset:4096
	ds_read_b128 v[210:213], v171 offset:5120
	ds_read_b128 v[214:217], v171 offset:6144
	ds_read_b128 v[218:221], v171 offset:7168
	s_waitcnt vmcnt(8)
	s_waitcnt lgkmcnt(0)
	s_barrier
	s_waitcnt lgkmcnt(0)
	v_mfma_f32_16x16x32_bf16 v[124:127], v[148:151], v[190:193], v[124:127]
	v_mfma_f32_16x16x32_bf16 v[124:127], v[152:155], v[194:197], v[124:127]
	v_mfma_f32_16x16x32_bf16 v[120:123], v[160:163], v[194:197], v[120:123]
	v_mfma_f32_16x16x32_bf16 v[120:123], v[156:159], v[190:193], v[120:123]
	v_mfma_f32_16x16x32_bf16 v[60:63], v[174:177], v[190:193], v[60:63]
	v_mfma_f32_16x16x32_bf16 v[60:63], v[178:181], v[194:197], v[60:63]
	v_mfma_f32_16x16x32_bf16 v[56:59], v[186:189], v[194:197], v[56:59]
	v_mfma_f32_16x16x32_bf16 v[56:59], v[182:185], v[190:193], v[56:59]
	v_mfma_f32_16x16x32_bf16 v[48:51], v[182:185], v[198:201], v[48:51]
	v_mfma_f32_16x16x32_bf16 v[48:51], v[186:189], v[202:205], v[48:51]
	v_mfma_f32_16x16x32_bf16 v[52:55], v[178:181], v[202:205], v[52:55]
	v_mfma_f32_16x16x32_bf16 v[52:55], v[174:177], v[198:201], v[52:55]
	v_mfma_f32_16x16x32_bf16 v[112:115], v[156:159], v[198:201], v[112:115]
	v_mfma_f32_16x16x32_bf16 v[112:115], v[160:163], v[202:205], v[112:115]
	v_mfma_f32_16x16x32_bf16 v[116:119], v[152:155], v[202:205], v[116:119]
	v_mfma_f32_16x16x32_bf16 v[116:119], v[148:151], v[198:201], v[116:119]
	v_mfma_f32_16x16x32_bf16 v[108:111], v[148:151], v[206:209], v[108:111]
	v_mfma_f32_16x16x32_bf16 v[108:111], v[152:155], v[210:213], v[108:111]
	v_mfma_f32_16x16x32_bf16 v[104:107], v[160:163], v[210:213], v[104:107]
	v_mfma_f32_16x16x32_bf16 v[104:107], v[156:159], v[206:209], v[104:107]
	v_mfma_f32_16x16x32_bf16 v[44:47], v[174:177], v[206:209], v[44:47]
	v_mfma_f32_16x16x32_bf16 v[44:47], v[178:181], v[210:213], v[44:47]
	v_mfma_f32_16x16x32_bf16 v[40:43], v[186:189], v[210:213], v[40:43]
	v_mfma_f32_16x16x32_bf16 v[40:43], v[182:185], v[206:209], v[40:43]
	v_mfma_f32_16x16x32_bf16 v[32:35], v[182:185], v[214:217], v[32:35]
	v_mfma_f32_16x16x32_bf16 v[32:35], v[186:189], v[218:221], v[32:35]
	v_mfma_f32_16x16x32_bf16 v[36:39], v[178:181], v[218:221], v[36:39]
	v_mfma_f32_16x16x32_bf16 v[36:39], v[174:177], v[214:217], v[36:39]
	v_mfma_f32_16x16x32_bf16 v[96:99], v[156:159], v[214:217], v[96:99]
	v_mfma_f32_16x16x32_bf16 v[96:99], v[160:163], v[218:221], v[96:99]
	v_mfma_f32_16x16x32_bf16 v[100:103], v[152:155], v[218:221], v[100:103]
	v_mfma_f32_16x16x32_bf16 v[100:103], v[148:151], v[214:217], v[100:103]
	s_barrier
	s_add_i32 s35, s55, s36
	v_lshl_add_u64 v[222:223], s[26:27], 0, v[130:131]
	s_mov_b32 m0, s35
	v_lshl_add_u64 v[224:225], s[26:27], 0, v[134:135]
	global_load_lds_dwordx4 v[222:223], off
	s_add_i32 m0, s35, 0x2000
	s_add_u32 s58, s26, 0x100000
	s_addc_u32 s59, s27, 0
	s_add_i32 s35, s56, s36
	global_load_lds_dwordx4 v[224:225], off
	v_lshl_add_u64 v[190:191], s[58:59], 0, v[130:131]
	s_mov_b32 m0, s35
	v_lshl_add_u64 v[226:227], s[28:29], 0, v[128:129]
	global_load_lds_dwordx4 v[190:191], off
	v_lshl_add_u64 v[190:191], s[58:59], 0, v[134:135]
	s_add_i32 m0, s35, 0x2000
	v_lshl_add_u64 v[228:229], s[28:29], 0, v[132:133]
	global_load_lds_dwordx4 v[190:191], off
	s_mov_b32 m0, s41
	s_nop 0
	global_load_lds_dwordx4 v[226:227], off
	s_mov_b32 m0, s42
	s_nop 0
	global_load_lds_dwordx4 v[228:229], off
	ds_read_b128 v[190:193], v171 offset:16384
	ds_read_b128 v[194:197], v171 offset:17408
	ds_read_b128 v[198:201], v171 offset:18432
	ds_read_b128 v[202:205], v171 offset:19456
	ds_read_b128 v[206:209], v171 offset:20480
	ds_read_b128 v[210:213], v171 offset:21504
	ds_read_b128 v[214:217], v171 offset:22528
	ds_read_b128 v[218:221], v171 offset:23552
	s_waitcnt vmcnt(8)
	s_waitcnt lgkmcnt(0)
	s_barrier
	s_waitcnt lgkmcnt(0)
	v_mfma_f32_16x16x32_bf16 v[92:95], v[148:151], v[190:193], v[92:95]
	v_mfma_f32_16x16x32_bf16 v[92:95], v[152:155], v[194:197], v[92:95]
	v_mfma_f32_16x16x32_bf16 v[88:91], v[160:163], v[194:197], v[88:91]
	v_mfma_f32_16x16x32_bf16 v[88:91], v[156:159], v[190:193], v[88:91]
	v_mfma_f32_16x16x32_bf16 v[28:31], v[174:177], v[190:193], v[28:31]
	v_mfma_f32_16x16x32_bf16 v[28:31], v[178:181], v[194:197], v[28:31]
	v_mfma_f32_16x16x32_bf16 v[24:27], v[186:189], v[194:197], v[24:27]
	v_mfma_f32_16x16x32_bf16 v[24:27], v[182:185], v[190:193], v[24:27]
	v_mfma_f32_16x16x32_bf16 v[16:19], v[182:185], v[198:201], v[16:19]
	v_mfma_f32_16x16x32_bf16 v[16:19], v[186:189], v[202:205], v[16:19]
	v_mfma_f32_16x16x32_bf16 v[20:23], v[178:181], v[202:205], v[20:23]
	v_mfma_f32_16x16x32_bf16 v[20:23], v[174:177], v[198:201], v[20:23]
	v_mfma_f32_16x16x32_bf16 v[80:83], v[156:159], v[198:201], v[80:83]
	v_mfma_f32_16x16x32_bf16 v[80:83], v[160:163], v[202:205], v[80:83]
	v_mfma_f32_16x16x32_bf16 v[84:87], v[152:155], v[202:205], v[84:87]
	v_mfma_f32_16x16x32_bf16 v[84:87], v[148:151], v[198:201], v[84:87]
	v_mfma_f32_16x16x32_bf16 v[76:79], v[148:151], v[206:209], v[76:79]
	v_mfma_f32_16x16x32_bf16 v[76:79], v[152:155], v[210:213], v[76:79]
	v_mfma_f32_16x16x32_bf16 v[72:75], v[160:163], v[210:213], v[72:75]
	v_mfma_f32_16x16x32_bf16 v[72:75], v[156:159], v[206:209], v[72:75]
	v_mfma_f32_16x16x32_bf16 v[12:15], v[174:177], v[206:209], v[12:15]
	v_mfma_f32_16x16x32_bf16 v[12:15], v[178:181], v[210:213], v[12:15]
	v_mfma_f32_16x16x32_bf16 v[8:11], v[186:189], v[210:213], v[8:11]
	v_mfma_f32_16x16x32_bf16 v[8:11], v[182:185], v[206:209], v[8:11]
	v_mfma_f32_16x16x32_bf16 v[0:3], v[182:185], v[214:217], v[0:3]
	v_mfma_f32_16x16x32_bf16 v[0:3], v[186:189], v[218:221], v[0:3]
	v_mfma_f32_16x16x32_bf16 v[4:7], v[178:181], v[218:221], v[4:7]
	v_mfma_f32_16x16x32_bf16 v[4:7], v[174:177], v[214:217], v[4:7]
	v_mfma_f32_16x16x32_bf16 v[64:67], v[156:159], v[214:217], v[64:67]
	v_mfma_f32_16x16x32_bf16 v[64:67], v[160:163], v[218:221], v[64:67]
	v_mfma_f32_16x16x32_bf16 v[68:71], v[152:155], v[218:221], v[68:71]
	v_mfma_f32_16x16x32_bf16 v[68:71], v[148:151], v[214:217], v[68:71]
	s_barrier
	s_add_i32 s35, 0, 0x18000
	v_add_u32_e32 v136, s35, v165
	s_add_i32 s57, 0, 0x1c000
	ds_read_b128 v[148:151], v136
	ds_read_b128 v[152:155], v136 offset:1024
	ds_read_b128 v[156:159], v136 offset:2048
	ds_read_b128 v[160:163], v136 offset:3072
	v_add_u32_e32 v136, s57, v165
	ds_read_b128 v[174:177], v136
	ds_read_b128 v[178:181], v136 offset:1024
	ds_read_b128 v[182:185], v136 offset:2048
	ds_read_b128 v[186:189], v136 offset:3072
	s_add_u32 s28, s28, 0x100000
	s_addc_u32 s29, s29, 0
	s_mov_b32 m0, s43
	v_lshl_add_u64 v[190:191], s[28:29], 0, v[128:129]
	global_load_lds_dwordx4 v[190:191], off
	v_lshl_add_u64 v[190:191], s[28:29], 0, v[132:133]
	s_mov_b32 m0, s44
	s_nop 0
	global_load_lds_dwordx4 v[190:191], off
	ds_read_b128 v[190:193], v171 offset:32768
	ds_read_b128 v[194:197], v171 offset:33792
	ds_read_b128 v[198:201], v171 offset:34816
	ds_read_b128 v[202:205], v171 offset:35840
	ds_read_b128 v[206:209], v171 offset:36864
	ds_read_b128 v[210:213], v171 offset:37888
	ds_read_b128 v[214:217], v171 offset:38912
	ds_read_b128 v[218:221], v171 offset:39936
	s_waitcnt vmcnt(8)
	s_waitcnt lgkmcnt(0)
	s_barrier
	s_waitcnt lgkmcnt(0)
	v_mfma_f32_16x16x32_bf16 v[124:127], v[148:151], v[190:193], v[124:127]
	v_mfma_f32_16x16x32_bf16 v[124:127], v[152:155], v[194:197], v[124:127]
	v_mfma_f32_16x16x32_bf16 v[120:123], v[160:163], v[194:197], v[120:123]
	v_mfma_f32_16x16x32_bf16 v[120:123], v[156:159], v[190:193], v[120:123]
	v_mfma_f32_16x16x32_bf16 v[60:63], v[174:177], v[190:193], v[60:63]
	v_mfma_f32_16x16x32_bf16 v[60:63], v[178:181], v[194:197], v[60:63]
	v_mfma_f32_16x16x32_bf16 v[56:59], v[186:189], v[194:197], v[56:59]
	v_mfma_f32_16x16x32_bf16 v[56:59], v[182:185], v[190:193], v[56:59]
	v_mfma_f32_16x16x32_bf16 v[48:51], v[182:185], v[198:201], v[48:51]
	v_mfma_f32_16x16x32_bf16 v[48:51], v[186:189], v[202:205], v[48:51]
	v_mfma_f32_16x16x32_bf16 v[52:55], v[178:181], v[202:205], v[52:55]
	v_mfma_f32_16x16x32_bf16 v[52:55], v[174:177], v[198:201], v[52:55]
	v_mfma_f32_16x16x32_bf16 v[112:115], v[156:159], v[198:201], v[112:115]
	v_mfma_f32_16x16x32_bf16 v[112:115], v[160:163], v[202:205], v[112:115]
	v_mfma_f32_16x16x32_bf16 v[116:119], v[152:155], v[202:205], v[116:119]
	v_mfma_f32_16x16x32_bf16 v[116:119], v[148:151], v[198:201], v[116:119]
	v_mfma_f32_16x16x32_bf16 v[108:111], v[148:151], v[206:209], v[108:111]
	v_mfma_f32_16x16x32_bf16 v[108:111], v[152:155], v[210:213], v[108:111]
	v_mfma_f32_16x16x32_bf16 v[104:107], v[160:163], v[210:213], v[104:107]
	v_mfma_f32_16x16x32_bf16 v[104:107], v[156:159], v[206:209], v[104:107]
	v_mfma_f32_16x16x32_bf16 v[44:47], v[174:177], v[206:209], v[44:47]
	v_mfma_f32_16x16x32_bf16 v[44:47], v[178:181], v[210:213], v[44:47]
	v_mfma_f32_16x16x32_bf16 v[40:43], v[186:189], v[210:213], v[40:43]
	v_mfma_f32_16x16x32_bf16 v[40:43], v[182:185], v[206:209], v[40:43]
	v_mfma_f32_16x16x32_bf16 v[32:35], v[182:185], v[214:217], v[32:35]
	v_mfma_f32_16x16x32_bf16 v[32:35], v[186:189], v[218:221], v[32:35]
	v_mfma_f32_16x16x32_bf16 v[36:39], v[178:181], v[218:221], v[36:39]
	v_mfma_f32_16x16x32_bf16 v[36:39], v[174:177], v[214:217], v[36:39]
	v_mfma_f32_16x16x32_bf16 v[96:99], v[156:159], v[214:217], v[96:99]
	v_mfma_f32_16x16x32_bf16 v[96:99], v[160:163], v[218:221], v[96:99]
	v_mfma_f32_16x16x32_bf16 v[100:103], v[152:155], v[218:221], v[100:103]
	v_mfma_f32_16x16x32_bf16 v[100:103], v[148:151], v[214:217], v[100:103]
	s_barrier
	s_add_i32 s28, s35, s36
	v_lshl_add_u64 v[190:191], v[222:223], 0, s[12:13]
	s_mov_b32 m0, s28
	s_nop 0
	global_load_lds_dwordx4 v[190:191], off
	s_add_i32 m0, s28, 0x2000
	s_add_u32 s26, s26, 0x100800
	v_lshl_add_u64 v[190:191], v[224:225], 0, s[12:13]
	s_addc_u32 s27, s27, 0
	s_add_i32 s28, s57, s36
	global_load_lds_dwordx4 v[190:191], off
	v_lshl_add_u64 v[190:191], s[26:27], 0, v[130:131]
	s_mov_b32 m0, s28
	s_nop 0
	global_load_lds_dwordx4 v[190:191], off
	v_lshl_add_u64 v[190:191], s[26:27], 0, v[134:135]
	s_add_i32 m0, s28, 0x2000
	s_nop 0
	global_load_lds_dwordx4 v[190:191], off
	v_lshl_add_u64 v[190:191], v[226:227], 0, s[12:13]
	s_mov_b32 m0, s49
	s_nop 0
	global_load_lds_dwordx4 v[190:191], off
	v_lshl_add_u64 v[190:191], v[228:229], 0, s[12:13]
	s_mov_b32 m0, s50
	s_nop 0
	global_load_lds_dwordx4 v[190:191], off
	ds_read_b128 v[190:193], v171 offset:49152
	ds_read_b128 v[194:197], v171 offset:50176
	ds_read_b128 v[198:201], v171 offset:51200
	ds_read_b128 v[202:205], v171 offset:52224
	ds_read_b128 v[206:209], v171 offset:53248
	ds_read_b128 v[210:213], v171 offset:54272
	ds_read_b128 v[214:217], v171 offset:55296
	ds_read_b128 v[218:221], v171 offset:56320
	s_waitcnt vmcnt(8)
	s_waitcnt lgkmcnt(0)
	s_barrier
	s_waitcnt lgkmcnt(0)
	v_mfma_f32_16x16x32_bf16 v[92:95], v[148:151], v[190:193], v[92:95]
	v_mfma_f32_16x16x32_bf16 v[92:95], v[152:155], v[194:197], v[92:95]
	v_mfma_f32_16x16x32_bf16 v[88:91], v[160:163], v[194:197], v[88:91]
	v_mfma_f32_16x16x32_bf16 v[88:91], v[156:159], v[190:193], v[88:91]
	v_mfma_f32_16x16x32_bf16 v[28:31], v[174:177], v[190:193], v[28:31]
	v_mfma_f32_16x16x32_bf16 v[28:31], v[178:181], v[194:197], v[28:31]
	v_mfma_f32_16x16x32_bf16 v[24:27], v[186:189], v[194:197], v[24:27]
	v_mfma_f32_16x16x32_bf16 v[24:27], v[182:185], v[190:193], v[24:27]
	v_mfma_f32_16x16x32_bf16 v[16:19], v[182:185], v[198:201], v[16:19]
	v_mfma_f32_16x16x32_bf16 v[16:19], v[186:189], v[202:205], v[16:19]
	v_mfma_f32_16x16x32_bf16 v[20:23], v[178:181], v[202:205], v[20:23]
	v_mfma_f32_16x16x32_bf16 v[20:23], v[174:177], v[198:201], v[20:23]
	v_mfma_f32_16x16x32_bf16 v[80:83], v[156:159], v[198:201], v[80:83]
	v_mfma_f32_16x16x32_bf16 v[80:83], v[160:163], v[202:205], v[80:83]
	v_mfma_f32_16x16x32_bf16 v[84:87], v[152:155], v[202:205], v[84:87]
	v_mfma_f32_16x16x32_bf16 v[84:87], v[148:151], v[198:201], v[84:87]
	v_mfma_f32_16x16x32_bf16 v[76:79], v[148:151], v[206:209], v[76:79]
	v_mfma_f32_16x16x32_bf16 v[76:79], v[152:155], v[210:213], v[76:79]
	v_mfma_f32_16x16x32_bf16 v[72:75], v[160:163], v[210:213], v[72:75]
	v_mfma_f32_16x16x32_bf16 v[72:75], v[156:159], v[206:209], v[72:75]
	v_mfma_f32_16x16x32_bf16 v[12:15], v[174:177], v[206:209], v[12:15]
	v_mfma_f32_16x16x32_bf16 v[12:15], v[178:181], v[210:213], v[12:15]
	v_mfma_f32_16x16x32_bf16 v[8:11], v[186:189], v[210:213], v[8:11]
	v_mfma_f32_16x16x32_bf16 v[8:11], v[182:185], v[206:209], v[8:11]
	v_mfma_f32_16x16x32_bf16 v[0:3], v[182:185], v[214:217], v[0:3]
	v_mfma_f32_16x16x32_bf16 v[0:3], v[186:189], v[218:221], v[0:3]
	v_mfma_f32_16x16x32_bf16 v[4:7], v[178:181], v[218:221], v[4:7]
	v_mfma_f32_16x16x32_bf16 v[4:7], v[174:177], v[214:217], v[4:7]
	v_mfma_f32_16x16x32_bf16 v[64:67], v[156:159], v[214:217], v[64:67]
	v_mfma_f32_16x16x32_bf16 v[64:67], v[160:163], v[218:221], v[64:67]
	v_mfma_f32_16x16x32_bf16 v[68:71], v[152:155], v[218:221], v[68:71]
	v_mfma_f32_16x16x32_bf16 v[68:71], v[148:151], v[214:217], v[68:71]
	s_barrier
	s_add_i32 s34, s34, 2
	s_add_u32 s6, s6, 0x1000
	s_addc_u32 s7, s7, 0
	s_add_u32 s30, s30, 0x1000
	s_addc_u32 s31, s31, 0
	s_cmp_gt_u32 s34, 61
	s_cbranch_scc0 .LBB0_200
	s_and_b64 vcc, exec, s[0:1]
	s_cbranch_vccz .LBB0_203
	s_barrier

.LBB0_333:
	ds_read_b128 v[144:147], v152
	ds_read_b128 v[156:159], v152 offset:1024
	ds_read_b128 v[160:163], v152 offset:2048
	ds_read_b128 v[164:167], v152 offset:3072
	ds_read_b128 v[168:171], v153
	ds_read_b128 v[172:175], v153 offset:1024
	ds_read_b128 v[176:179], v153 offset:2048
	ds_read_b128 v[180:183], v153 offset:3072
	s_add_u32 s28, s24, 0x100
	s_addc_u32 s29, s25, 0
	s_cmp_eq_u32 s56, 60
	s_cselect_b32 s35, s13, s29
	s_cselect_b32 s34, s52, s28
	s_cselect_b32 s31, s11, s55
	s_cselect_b32 s30, s53, s54
	v_lshl_add_u64 v[184:185], s[24:25], 0, v[136:137]
	s_add_i32 m0, s21, 0xc000
	s_nop 0
	global_load_lds_dwordx4 v[184:185], off
	v_lshl_add_u64 v[184:185], s[24:25], 0, v[138:139]
	s_add_i32 m0, s21, 0xe000
	s_nop 0
	global_load_lds_dwordx4 v[184:185], off
	ds_read_b128 v[184:187], v154
	ds_read_b128 v[188:191], v154 offset:1024
	ds_read_b128 v[192:195], v154 offset:2048
	ds_read_b128 v[196:199], v154 offset:3072
	ds_read_b128 v[200:203], v154 offset:4096
	ds_read_b128 v[204:207], v154 offset:5120
	ds_read_b128 v[208:211], v154 offset:6144
	ds_read_b128 v[212:215], v154 offset:7168
	s_waitcnt vmcnt(8)
	s_waitcnt lgkmcnt(0)
	s_barrier
	s_waitcnt lgkmcnt(0)
	v_mfma_f32_16x16x32_bf16 v[124:127], v[144:147], v[184:187], v[124:127]
	v_mfma_f32_16x16x32_bf16 v[124:127], v[156:159], v[188:191], v[124:127]
	v_mfma_f32_16x16x32_bf16 v[120:123], v[164:167], v[188:191], v[120:123]
	v_mfma_f32_16x16x32_bf16 v[120:123], v[160:163], v[184:187], v[120:123]
	v_mfma_f32_16x16x32_bf16 v[112:115], v[168:171], v[184:187], v[112:115]
	v_mfma_f32_16x16x32_bf16 v[112:115], v[172:175], v[188:191], v[112:115]
	v_mfma_f32_16x16x32_bf16 v[104:107], v[180:183], v[188:191], v[104:107]
	v_mfma_f32_16x16x32_bf16 v[104:107], v[176:179], v[184:187], v[104:107]
	v_mfma_f32_16x16x32_bf16 v[88:91], v[176:179], v[192:195], v[88:91]
	v_mfma_f32_16x16x32_bf16 v[88:91], v[180:183], v[196:199], v[88:91]
	v_mfma_f32_16x16x32_bf16 v[96:99], v[172:175], v[196:199], v[96:99]
	v_mfma_f32_16x16x32_bf16 v[96:99], v[168:171], v[192:195], v[96:99]
	v_mfma_f32_16x16x32_bf16 v[108:111], v[160:163], v[192:195], v[108:111]
	v_mfma_f32_16x16x32_bf16 v[108:111], v[164:167], v[196:199], v[108:111]
	v_mfma_f32_16x16x32_bf16 v[116:119], v[156:159], v[196:199], v[116:119]
	v_mfma_f32_16x16x32_bf16 v[116:119], v[144:147], v[192:195], v[116:119]
	v_mfma_f32_16x16x32_bf16 v[100:103], v[144:147], v[200:203], v[100:103]
	v_mfma_f32_16x16x32_bf16 v[100:103], v[156:159], v[204:207], v[100:103]
	v_mfma_f32_16x16x32_bf16 v[92:95], v[164:167], v[204:207], v[92:95]
	v_mfma_f32_16x16x32_bf16 v[92:95], v[160:163], v[200:203], v[92:95]
	v_mfma_f32_16x16x32_bf16 v[80:83], v[168:171], v[200:203], v[80:83]
	v_mfma_f32_16x16x32_bf16 v[80:83], v[172:175], v[204:207], v[80:83]
	v_mfma_f32_16x16x32_bf16 v[72:75], v[180:183], v[204:207], v[72:75]
	v_mfma_f32_16x16x32_bf16 v[72:75], v[176:179], v[200:203], v[72:75]
	v_mfma_f32_16x16x32_bf16 v[64:67], v[176:179], v[208:211], v[64:67]
	v_mfma_f32_16x16x32_bf16 v[64:67], v[180:183], v[212:215], v[64:67]
	v_mfma_f32_16x16x32_bf16 v[68:71], v[172:175], v[212:215], v[68:71]
	v_mfma_f32_16x16x32_bf16 v[68:71], v[168:171], v[208:211], v[68:71]
	v_mfma_f32_16x16x32_bf16 v[76:79], v[160:163], v[208:211], v[76:79]
	v_mfma_f32_16x16x32_bf16 v[76:79], v[164:167], v[212:215], v[76:79]
	v_mfma_f32_16x16x32_bf16 v[84:87], v[156:159], v[212:215], v[84:87]
	v_mfma_f32_16x16x32_bf16 v[84:87], v[144:147], v[208:211], v[84:87]
	s_barrier
	s_add_i32 s24, s49, s41
	v_lshl_add_u64 v[216:217], s[30:31], 0, v[130:131]
	s_mov_b32 m0, s24
	v_lshl_add_u64 v[218:219], s[30:31], 0, v[134:135]
	global_load_lds_dwordx4 v[216:217], off
	s_add_i32 m0, s24, 0x2000
	s_add_u32 s24, s30, 0x100000
	s_addc_u32 s25, s31, 0
	s_add_i32 s57, s50, s41
	global_load_lds_dwordx4 v[218:219], off
	v_lshl_add_u64 v[184:185], s[24:25], 0, v[130:131]
	s_mov_b32 m0, s57
	v_lshl_add_u64 v[220:221], s[34:35], 0, v[128:129]
	global_load_lds_dwordx4 v[184:185], off
	v_lshl_add_u64 v[184:185], s[24:25], 0, v[134:135]
	s_add_i32 m0, s57, 0x2000
	v_lshl_add_u64 v[222:223], s[34:35], 0, v[132:133]
	global_load_lds_dwordx4 v[184:185], off
	s_mov_b32 m0, s21
	s_nop 0
	global_load_lds_dwordx4 v[220:221], off
	s_mov_b32 m0, s42
	s_nop 0
	global_load_lds_dwordx4 v[222:223], off
	ds_read_b128 v[184:187], v154 offset:16384
	ds_read_b128 v[188:191], v154 offset:17408
	ds_read_b128 v[192:195], v154 offset:18432
	ds_read_b128 v[196:199], v154 offset:19456
	ds_read_b128 v[200:203], v154 offset:20480
	ds_read_b128 v[204:207], v154 offset:21504
	ds_read_b128 v[208:211], v154 offset:22528
	ds_read_b128 v[212:215], v154 offset:23552
	s_waitcnt vmcnt(8)
	s_waitcnt lgkmcnt(0)
	s_barrier
	s_waitcnt lgkmcnt(0)
	v_mfma_f32_16x16x32_bf16 v[60:63], v[144:147], v[184:187], v[60:63]
	v_mfma_f32_16x16x32_bf16 v[60:63], v[156:159], v[188:191], v[60:63]
	v_mfma_f32_16x16x32_bf16 v[56:59], v[164:167], v[188:191], v[56:59]
	v_mfma_f32_16x16x32_bf16 v[56:59], v[160:163], v[184:187], v[56:59]
	v_mfma_f32_16x16x32_bf16 v[48:51], v[168:171], v[184:187], v[48:51]
	v_mfma_f32_16x16x32_bf16 v[48:51], v[172:175], v[188:191], v[48:51]
	v_mfma_f32_16x16x32_bf16 v[40:43], v[180:183], v[188:191], v[40:43]
	v_mfma_f32_16x16x32_bf16 v[40:43], v[176:179], v[184:187], v[40:43]
	v_mfma_f32_16x16x32_bf16 v[24:27], v[176:179], v[192:195], v[24:27]
	v_mfma_f32_16x16x32_bf16 v[24:27], v[180:183], v[196:199], v[24:27]
	v_mfma_f32_16x16x32_bf16 v[32:35], v[172:175], v[196:199], v[32:35]
	v_mfma_f32_16x16x32_bf16 v[32:35], v[168:171], v[192:195], v[32:35]
	v_mfma_f32_16x16x32_bf16 v[44:47], v[160:163], v[192:195], v[44:47]
	v_mfma_f32_16x16x32_bf16 v[44:47], v[164:167], v[196:199], v[44:47]
	v_mfma_f32_16x16x32_bf16 v[52:55], v[156:159], v[196:199], v[52:55]
	v_mfma_f32_16x16x32_bf16 v[52:55], v[144:147], v[192:195], v[52:55]
	v_mfma_f32_16x16x32_bf16 v[36:39], v[144:147], v[200:203], v[36:39]
	v_mfma_f32_16x16x32_bf16 v[36:39], v[156:159], v[204:207], v[36:39]
	v_mfma_f32_16x16x32_bf16 v[28:31], v[164:167], v[204:207], v[28:31]
	v_mfma_f32_16x16x32_bf16 v[28:31], v[160:163], v[200:203], v[28:31]
	v_mfma_f32_16x16x32_bf16 v[16:19], v[168:171], v[200:203], v[16:19]
	v_mfma_f32_16x16x32_bf16 v[16:19], v[172:175], v[204:207], v[16:19]
	v_mfma_f32_16x16x32_bf16 v[8:11], v[180:183], v[204:207], v[8:11]
	v_mfma_f32_16x16x32_bf16 v[8:11], v[176:179], v[200:203], v[8:11]
	v_mfma_f32_16x16x32_bf16 v[0:3], v[176:179], v[208:211], v[0:3]
	v_mfma_f32_16x16x32_bf16 v[0:3], v[180:183], v[212:215], v[0:3]
	v_mfma_f32_16x16x32_bf16 v[4:7], v[172:175], v[212:215], v[4:7]
	v_mfma_f32_16x16x32_bf16 v[4:7], v[168:171], v[208:211], v[4:7]
	v_mfma_f32_16x16x32_bf16 v[12:15], v[160:163], v[208:211], v[12:15]
	v_mfma_f32_16x16x32_bf16 v[12:15], v[164:167], v[212:215], v[12:15]
	v_mfma_f32_16x16x32_bf16 v[20:23], v[156:159], v[212:215], v[20:23]
	v_mfma_f32_16x16x32_bf16 v[20:23], v[144:147], v[208:211], v[20:23]
	s_barrier
	s_add_i32 s57, 0, 0x18000
	v_add_u32_e32 v155, s57, v149
	s_add_i32 s58, 0, 0x1c000
	ds_read_b128 v[144:147], v155
	ds_read_b128 v[156:159], v155 offset:1024
	ds_read_b128 v[160:163], v155 offset:2048
	ds_read_b128 v[164:167], v155 offset:3072
	v_add_u32_e32 v155, s58, v149
	ds_read_b128 v[168:171], v155
	ds_read_b128 v[172:175], v155 offset:1024
	ds_read_b128 v[176:179], v155 offset:2048
	ds_read_b128 v[180:183], v155 offset:3072
	s_add_u32 s24, s34, 0x100000
	s_addc_u32 s25, s35, 0
	s_mov_b32 m0, s43
	v_lshl_add_u64 v[184:185], s[24:25], 0, v[128:129]
	global_load_lds_dwordx4 v[184:185], off
	v_lshl_add_u64 v[184:185], s[24:25], 0, v[132:133]
	s_mov_b32 m0, s44
	s_nop 0
	global_load_lds_dwordx4 v[184:185], off
	ds_read_b128 v[184:187], v154 offset:32768
	ds_read_b128 v[188:191], v154 offset:33792
	ds_read_b128 v[192:195], v154 offset:34816
	ds_read_b128 v[196:199], v154 offset:35840
	ds_read_b128 v[200:203], v154 offset:36864
	ds_read_b128 v[204:207], v154 offset:37888
	ds_read_b128 v[208:211], v154 offset:38912
	ds_read_b128 v[212:215], v154 offset:39936
	s_waitcnt vmcnt(8)
	s_waitcnt lgkmcnt(0)
	s_barrier
	s_waitcnt lgkmcnt(0)
	v_mfma_f32_16x16x32_bf16 v[124:127], v[144:147], v[184:187], v[124:127]
	v_mfma_f32_16x16x32_bf16 v[124:127], v[156:159], v[188:191], v[124:127]
	v_mfma_f32_16x16x32_bf16 v[120:123], v[164:167], v[188:191], v[120:123]
	v_mfma_f32_16x16x32_bf16 v[120:123], v[160:163], v[184:187], v[120:123]
	v_mfma_f32_16x16x32_bf16 v[112:115], v[168:171], v[184:187], v[112:115]
	v_mfma_f32_16x16x32_bf16 v[112:115], v[172:175], v[188:191], v[112:115]
	v_mfma_f32_16x16x32_bf16 v[104:107], v[180:183], v[188:191], v[104:107]
	v_mfma_f32_16x16x32_bf16 v[104:107], v[176:179], v[184:187], v[104:107]
	v_mfma_f32_16x16x32_bf16 v[88:91], v[176:179], v[192:195], v[88:91]
	v_mfma_f32_16x16x32_bf16 v[88:91], v[180:183], v[196:199], v[88:91]
	v_mfma_f32_16x16x32_bf16 v[96:99], v[172:175], v[196:199], v[96:99]
	v_mfma_f32_16x16x32_bf16 v[96:99], v[168:171], v[192:195], v[96:99]
	v_mfma_f32_16x16x32_bf16 v[108:111], v[160:163], v[192:195], v[108:111]
	v_mfma_f32_16x16x32_bf16 v[108:111], v[164:167], v[196:199], v[108:111]
	v_mfma_f32_16x16x32_bf16 v[116:119], v[156:159], v[196:199], v[116:119]
	v_mfma_f32_16x16x32_bf16 v[116:119], v[144:147], v[192:195], v[116:119]
	v_mfma_f32_16x16x32_bf16 v[100:103], v[144:147], v[200:203], v[100:103]
	v_mfma_f32_16x16x32_bf16 v[100:103], v[156:159], v[204:207], v[100:103]
	v_mfma_f32_16x16x32_bf16 v[92:95], v[164:167], v[204:207], v[92:95]
	v_mfma_f32_16x16x32_bf16 v[92:95], v[160:163], v[200:203], v[92:95]
	v_mfma_f32_16x16x32_bf16 v[80:83], v[168:171], v[200:203], v[80:83]
	v_mfma_f32_16x16x32_bf16 v[80:83], v[172:175], v[204:207], v[80:83]
	v_mfma_f32_16x16x32_bf16 v[72:75], v[180:183], v[204:207], v[72:75]
	v_mfma_f32_16x16x32_bf16 v[72:75], v[176:179], v[200:203], v[72:75]
	v_mfma_f32_16x16x32_bf16 v[64:67], v[176:179], v[208:211], v[64:67]
	v_mfma_f32_16x16x32_bf16 v[64:67], v[180:183], v[212:215], v[64:67]
	v_mfma_f32_16x16x32_bf16 v[68:71], v[172:175], v[212:215], v[68:71]
	v_mfma_f32_16x16x32_bf16 v[68:71], v[168:171], v[208:211], v[68:71]
	v_mfma_f32_16x16x32_bf16 v[76:79], v[160:163], v[208:211], v[76:79]
	v_mfma_f32_16x16x32_bf16 v[76:79], v[164:167], v[212:215], v[76:79]
	v_mfma_f32_16x16x32_bf16 v[84:87], v[156:159], v[212:215], v[84:87]
	v_mfma_f32_16x16x32_bf16 v[84:87], v[144:147], v[208:211], v[84:87]
	s_barrier
	s_add_i32 s24, s57, s41
	v_lshl_add_u64 v[184:185], v[216:217], 0, s[8:9]
	s_mov_b32 m0, s24
	s_nop 0
	global_load_lds_dwordx4 v[184:185], off
	s_add_i32 m0, s24, 0x2000
	s_add_u32 s24, s30, 0x100080
	v_lshl_add_u64 v[184:185], v[218:219], 0, s[8:9]
	s_addc_u32 s25, s31, 0
	s_add_i32 s30, s58, s41
	global_load_lds_dwordx4 v[184:185], off
	v_lshl_add_u64 v[184:185], s[24:25], 0, v[130:131]
	s_mov_b32 m0, s30
	s_nop 0
	global_load_lds_dwordx4 v[184:185], off
	v_lshl_add_u64 v[184:185], s[24:25], 0, v[134:135]
	s_add_i32 m0, s30, 0x2000
	s_nop 0
	global_load_lds_dwordx4 v[184:185], off
	v_lshl_add_u64 v[184:185], v[220:221], 0, s[8:9]
	s_mov_b32 m0, s46
	s_nop 0
	global_load_lds_dwordx4 v[184:185], off
	v_lshl_add_u64 v[184:185], v[222:223], 0, s[8:9]
	s_mov_b32 m0, s47
	s_nop 0
	global_load_lds_dwordx4 v[184:185], off
	ds_read_b128 v[184:187], v154 offset:49152
	ds_read_b128 v[188:191], v154 offset:50176
	ds_read_b128 v[192:195], v154 offset:51200
	ds_read_b128 v[196:199], v154 offset:52224
	ds_read_b128 v[200:203], v154 offset:53248
	ds_read_b128 v[204:207], v154 offset:54272
	ds_read_b128 v[208:211], v154 offset:55296
	ds_read_b128 v[212:215], v154 offset:56320
	s_waitcnt vmcnt(8)
	s_waitcnt lgkmcnt(0)
	s_barrier
	s_waitcnt lgkmcnt(0)
	v_mfma_f32_16x16x32_bf16 v[60:63], v[144:147], v[184:187], v[60:63]
	v_mfma_f32_16x16x32_bf16 v[60:63], v[156:159], v[188:191], v[60:63]
	v_mfma_f32_16x16x32_bf16 v[56:59], v[164:167], v[188:191], v[56:59]
	v_mfma_f32_16x16x32_bf16 v[56:59], v[160:163], v[184:187], v[56:59]
	v_mfma_f32_16x16x32_bf16 v[48:51], v[168:171], v[184:187], v[48:51]
	v_mfma_f32_16x16x32_bf16 v[48:51], v[172:175], v[188:191], v[48:51]
	v_mfma_f32_16x16x32_bf16 v[40:43], v[180:183], v[188:191], v[40:43]
	v_mfma_f32_16x16x32_bf16 v[40:43], v[176:179], v[184:187], v[40:43]
	v_mfma_f32_16x16x32_bf16 v[24:27], v[176:179], v[192:195], v[24:27]
	v_mfma_f32_16x16x32_bf16 v[24:27], v[180:183], v[196:199], v[24:27]
	v_mfma_f32_16x16x32_bf16 v[32:35], v[172:175], v[196:199], v[32:35]
	v_mfma_f32_16x16x32_bf16 v[32:35], v[168:171], v[192:195], v[32:35]
	v_mfma_f32_16x16x32_bf16 v[44:47], v[160:163], v[192:195], v[44:47]
	v_mfma_f32_16x16x32_bf16 v[44:47], v[164:167], v[196:199], v[44:47]
	v_mfma_f32_16x16x32_bf16 v[52:55], v[156:159], v[196:199], v[52:55]
	v_mfma_f32_16x16x32_bf16 v[52:55], v[144:147], v[192:195], v[52:55]
	v_mfma_f32_16x16x32_bf16 v[36:39], v[144:147], v[200:203], v[36:39]
	v_mfma_f32_16x16x32_bf16 v[36:39], v[156:159], v[204:207], v[36:39]
	v_mfma_f32_16x16x32_bf16 v[28:31], v[164:167], v[204:207], v[28:31]
	v_mfma_f32_16x16x32_bf16 v[28:31], v[160:163], v[200:203], v[28:31]
	v_mfma_f32_16x16x32_bf16 v[16:19], v[168:171], v[200:203], v[16:19]
	v_mfma_f32_16x16x32_bf16 v[16:19], v[172:175], v[204:207], v[16:19]
	v_mfma_f32_16x16x32_bf16 v[8:11], v[180:183], v[204:207], v[8:11]
	v_mfma_f32_16x16x32_bf16 v[8:11], v[176:179], v[200:203], v[8:11]
	v_mfma_f32_16x16x32_bf16 v[0:3], v[176:179], v[208:211], v[0:3]
	v_mfma_f32_16x16x32_bf16 v[0:3], v[180:183], v[212:215], v[0:3]
	v_mfma_f32_16x16x32_bf16 v[4:7], v[172:175], v[212:215], v[4:7]
	v_mfma_f32_16x16x32_bf16 v[4:7], v[168:171], v[208:211], v[4:7]
	v_mfma_f32_16x16x32_bf16 v[12:15], v[160:163], v[208:211], v[12:15]
	v_mfma_f32_16x16x32_bf16 v[12:15], v[164:167], v[212:215], v[12:15]
	v_mfma_f32_16x16x32_bf16 v[20:23], v[156:159], v[212:215], v[20:23]
	v_mfma_f32_16x16x32_bf16 v[20:23], v[144:147], v[208:211], v[20:23]
	s_barrier
	s_add_i32 s56, s56, 2
	s_add_u32 s54, s54, 0x100
	s_addc_u32 s55, s55, 0
	s_cmp_gt_u32 s56, 61
	s_mov_b64 s[24:25], s[28:29]
	s_cbranch_scc0 .LBB0_333
	s_and_b64 vcc, exec, s[0:1]
	s_cbranch_vccz .LBB0_336
	s_barrier

.LBB0_1202:
	ds_read_b128 v[128:131], v176
	ds_read_b128 v[132:135], v176 offset:1024
	ds_read_b128 v[136:139], v176 offset:2048
	ds_read_b128 v[140:143], v176 offset:3072
	ds_read_b128 v[144:147], v177
	ds_read_b128 v[148:151], v177 offset:1024
	ds_read_b128 v[180:183], v177 offset:2048
	ds_read_b128 v[184:187], v177 offset:3072
	s_add_u32 s30, s28, 0xfff00080
	s_addc_u32 s31, s29, -1
	s_cmp_eq_u32 s40, 60
	s_cselect_b32 s35, s23, s31
	s_cselect_b32 s34, s36, s30
	s_cselect_b32 s31, s21, s39
	s_cselect_b32 s30, s37, s38
	v_lshl_add_u64 v[172:173], s[28:29], 0, v[164:165]
	s_add_i32 m0, s7, 0xc000
	s_nop 0
	global_load_lds_dwordx4 v[172:173], off
	v_lshl_add_u64 v[172:173], s[28:29], 0, v[166:167]
	s_add_i32 m0, s7, 0xe000
	s_nop 0
	global_load_lds_dwordx4 v[172:173], off
	ds_read_b128 v[188:191], v178
	ds_read_b128 v[192:195], v178 offset:1024
	ds_read_b128 v[196:199], v178 offset:2048
	ds_read_b128 v[200:203], v178 offset:3072
	ds_read_b128 v[204:207], v178 offset:4096
	ds_read_b128 v[208:211], v178 offset:5120
	ds_read_b128 v[212:215], v178 offset:6144
	ds_read_b128 v[216:219], v178 offset:7168
	s_waitcnt vmcnt(8)
	s_waitcnt lgkmcnt(0)
	s_barrier
	s_waitcnt lgkmcnt(0)
	v_mfma_f32_16x16x32_bf16 v[124:127], v[128:131], v[188:191], v[124:127]
	v_mfma_f32_16x16x32_bf16 v[124:127], v[132:135], v[192:195], v[124:127]
	v_mfma_f32_16x16x32_bf16 v[120:123], v[140:143], v[192:195], v[120:123]
	v_mfma_f32_16x16x32_bf16 v[120:123], v[136:139], v[188:191], v[120:123]
	v_mfma_f32_16x16x32_bf16 v[116:119], v[144:147], v[188:191], v[116:119]
	v_mfma_f32_16x16x32_bf16 v[116:119], v[148:151], v[192:195], v[116:119]
	v_mfma_f32_16x16x32_bf16 v[112:115], v[184:187], v[192:195], v[112:115]
	v_mfma_f32_16x16x32_bf16 v[112:115], v[180:183], v[188:191], v[112:115]
	v_mfma_f32_16x16x32_bf16 v[96:99], v[180:183], v[196:199], v[96:99]
	v_mfma_f32_16x16x32_bf16 v[96:99], v[184:187], v[200:203], v[96:99]
	v_mfma_f32_16x16x32_bf16 v[100:103], v[148:151], v[200:203], v[100:103]
	v_mfma_f32_16x16x32_bf16 v[100:103], v[144:147], v[196:199], v[100:103]
	v_mfma_f32_16x16x32_bf16 v[104:107], v[136:139], v[196:199], v[104:107]
	v_mfma_f32_16x16x32_bf16 v[104:107], v[140:143], v[200:203], v[104:107]
	v_mfma_f32_16x16x32_bf16 v[108:111], v[132:135], v[200:203], v[108:111]
	v_mfma_f32_16x16x32_bf16 v[108:111], v[128:131], v[196:199], v[108:111]
	v_mfma_f32_16x16x32_bf16 v[92:95], v[128:131], v[204:207], v[92:95]
	v_mfma_f32_16x16x32_bf16 v[92:95], v[132:135], v[208:211], v[92:95]
	v_mfma_f32_16x16x32_bf16 v[88:91], v[140:143], v[208:211], v[88:91]
	v_mfma_f32_16x16x32_bf16 v[88:91], v[136:139], v[204:207], v[88:91]
	v_mfma_f32_16x16x32_bf16 v[84:87], v[144:147], v[204:207], v[84:87]
	v_mfma_f32_16x16x32_bf16 v[84:87], v[148:151], v[208:211], v[84:87]
	v_mfma_f32_16x16x32_bf16 v[80:83], v[184:187], v[208:211], v[80:83]
	v_mfma_f32_16x16x32_bf16 v[80:83], v[180:183], v[204:207], v[80:83]
	v_mfma_f32_16x16x32_bf16 v[64:67], v[180:183], v[212:215], v[64:67]
	v_mfma_f32_16x16x32_bf16 v[64:67], v[184:187], v[216:219], v[64:67]
	v_mfma_f32_16x16x32_bf16 v[68:71], v[148:151], v[216:219], v[68:71]
	v_mfma_f32_16x16x32_bf16 v[68:71], v[144:147], v[212:215], v[68:71]
	v_mfma_f32_16x16x32_bf16 v[72:75], v[136:139], v[212:215], v[72:75]
	v_mfma_f32_16x16x32_bf16 v[72:75], v[140:143], v[216:219], v[72:75]
	v_mfma_f32_16x16x32_bf16 v[76:79], v[132:135], v[216:219], v[76:79]
	v_mfma_f32_16x16x32_bf16 v[76:79], v[128:131], v[212:215], v[76:79]
	s_barrier
	s_add_i32 s41, s68, s33
	v_lshl_add_u64 v[172:173], s[30:31], 0, v[154:155]
	s_mov_b32 m0, s41
	v_lshl_add_u64 v[220:221], s[30:31], 0, v[158:159]
	global_load_lds_dwordx4 v[172:173], off
	s_add_i32 m0, s41, 0x2000
	s_add_u32 s42, s30, 0x100000
	s_addc_u32 s43, s31, 0
	s_add_i32 s41, s69, s33
	global_load_lds_dwordx4 v[220:221], off
	v_lshl_add_u64 v[188:189], s[42:43], 0, v[154:155]
	s_mov_b32 m0, s41
	v_lshl_add_u64 v[222:223], s[34:35], 0, v[152:153]
	global_load_lds_dwordx4 v[188:189], off
	v_lshl_add_u64 v[188:189], s[42:43], 0, v[158:159]
	s_add_i32 m0, s41, 0x2000
	v_lshl_add_u64 v[224:225], s[34:35], 0, v[156:157]
	global_load_lds_dwordx4 v[188:189], off
	s_mov_b32 m0, s7
	s_nop 0
	global_load_lds_dwordx4 v[222:223], off
	s_mov_b32 m0, s59
	s_nop 0
	global_load_lds_dwordx4 v[224:225], off
	ds_read_b128 v[188:191], v178 offset:16384
	ds_read_b128 v[192:195], v178 offset:17408
	ds_read_b128 v[196:199], v178 offset:18432
	ds_read_b128 v[200:203], v178 offset:19456
	ds_read_b128 v[204:207], v178 offset:20480
	ds_read_b128 v[208:211], v178 offset:21504
	ds_read_b128 v[212:215], v178 offset:22528
	ds_read_b128 v[216:219], v178 offset:23552
	s_waitcnt vmcnt(8)
	s_waitcnt lgkmcnt(0)
	s_barrier
	s_waitcnt lgkmcnt(0)
	v_mfma_f32_16x16x32_bf16 v[60:63], v[128:131], v[188:191], v[60:63]
	v_mfma_f32_16x16x32_bf16 v[60:63], v[132:135], v[192:195], v[60:63]
	v_mfma_f32_16x16x32_bf16 v[56:59], v[140:143], v[192:195], v[56:59]
	v_mfma_f32_16x16x32_bf16 v[56:59], v[136:139], v[188:191], v[56:59]
	v_mfma_f32_16x16x32_bf16 v[52:55], v[144:147], v[188:191], v[52:55]
	v_mfma_f32_16x16x32_bf16 v[52:55], v[148:151], v[192:195], v[52:55]
	v_mfma_f32_16x16x32_bf16 v[48:51], v[184:187], v[192:195], v[48:51]
	v_mfma_f32_16x16x32_bf16 v[48:51], v[180:183], v[188:191], v[48:51]
	v_mfma_f32_16x16x32_bf16 v[32:35], v[180:183], v[196:199], v[32:35]
	v_mfma_f32_16x16x32_bf16 v[32:35], v[184:187], v[200:203], v[32:35]
	v_mfma_f32_16x16x32_bf16 v[36:39], v[148:151], v[200:203], v[36:39]
	v_mfma_f32_16x16x32_bf16 v[36:39], v[144:147], v[196:199], v[36:39]
	v_mfma_f32_16x16x32_bf16 v[40:43], v[136:139], v[196:199], v[40:43]
	v_mfma_f32_16x16x32_bf16 v[40:43], v[140:143], v[200:203], v[40:43]
	v_mfma_f32_16x16x32_bf16 v[44:47], v[132:135], v[200:203], v[44:47]
	v_mfma_f32_16x16x32_bf16 v[44:47], v[128:131], v[196:199], v[44:47]
	v_mfma_f32_16x16x32_bf16 v[28:31], v[128:131], v[204:207], v[28:31]
	v_mfma_f32_16x16x32_bf16 v[28:31], v[132:135], v[208:211], v[28:31]
	v_mfma_f32_16x16x32_bf16 v[24:27], v[140:143], v[208:211], v[24:27]
	v_mfma_f32_16x16x32_bf16 v[24:27], v[136:139], v[204:207], v[24:27]
	v_mfma_f32_16x16x32_bf16 v[20:23], v[144:147], v[204:207], v[20:23]
	v_mfma_f32_16x16x32_bf16 v[20:23], v[148:151], v[208:211], v[20:23]
	v_mfma_f32_16x16x32_bf16 v[16:19], v[184:187], v[208:211], v[16:19]
	v_mfma_f32_16x16x32_bf16 v[16:19], v[180:183], v[204:207], v[16:19]
	v_mfma_f32_16x16x32_bf16 v[0:3], v[180:183], v[212:215], v[0:3]
	v_mfma_f32_16x16x32_bf16 v[0:3], v[184:187], v[216:219], v[0:3]
	v_mfma_f32_16x16x32_bf16 v[4:7], v[148:151], v[216:219], v[4:7]
	v_mfma_f32_16x16x32_bf16 v[4:7], v[144:147], v[212:215], v[4:7]
	v_mfma_f32_16x16x32_bf16 v[8:11], v[136:139], v[212:215], v[8:11]
	v_mfma_f32_16x16x32_bf16 v[8:11], v[140:143], v[216:219], v[8:11]
	v_mfma_f32_16x16x32_bf16 v[12:15], v[132:135], v[216:219], v[12:15]
	v_mfma_f32_16x16x32_bf16 v[12:15], v[128:131], v[212:215], v[12:15]
	s_barrier
	s_add_i32 s41, 0, 0x18000
	s_add_i32 s42, 0, 0x1c000
	v_add_u32_e32 v140, s41, v174
	v_add_u32_e32 v184, s42, v174
	ds_read_b128 v[128:131], v140
	ds_read_b128 v[132:135], v140 offset:1024
	ds_read_b128 v[136:139], v140 offset:2048
	ds_read_b128 v[140:143], v140 offset:3072
	ds_read_b128 v[144:147], v184
	ds_read_b128 v[148:151], v184 offset:1024
	ds_read_b128 v[180:183], v184 offset:2048
	ds_read_b128 v[184:187], v184 offset:3072
	s_add_u32 s34, s34, 0x100000
	s_addc_u32 s35, s35, 0
	s_mov_b32 m0, s60
	v_lshl_add_u64 v[188:189], s[34:35], 0, v[152:153]
	global_load_lds_dwordx4 v[188:189], off
	v_lshl_add_u64 v[188:189], s[34:35], 0, v[156:157]
	s_mov_b32 m0, s61
	s_nop 0
	global_load_lds_dwordx4 v[188:189], off
	ds_read_b128 v[188:191], v178 offset:32768
	ds_read_b128 v[192:195], v178 offset:33792
	ds_read_b128 v[196:199], v178 offset:34816
	ds_read_b128 v[200:203], v178 offset:35840
	ds_read_b128 v[204:207], v178 offset:36864
	ds_read_b128 v[208:211], v178 offset:37888
	ds_read_b128 v[212:215], v178 offset:38912
	ds_read_b128 v[216:219], v178 offset:39936
	s_waitcnt vmcnt(8)
	s_waitcnt lgkmcnt(0)
	s_barrier
	s_waitcnt lgkmcnt(0)
	v_mfma_f32_16x16x32_bf16 v[124:127], v[128:131], v[188:191], v[124:127]
	v_mfma_f32_16x16x32_bf16 v[124:127], v[132:135], v[192:195], v[124:127]
	v_mfma_f32_16x16x32_bf16 v[120:123], v[140:143], v[192:195], v[120:123]
	v_mfma_f32_16x16x32_bf16 v[120:123], v[136:139], v[188:191], v[120:123]
	v_mfma_f32_16x16x32_bf16 v[116:119], v[144:147], v[188:191], v[116:119]
	v_mfma_f32_16x16x32_bf16 v[116:119], v[148:151], v[192:195], v[116:119]
	v_mfma_f32_16x16x32_bf16 v[112:115], v[184:187], v[192:195], v[112:115]
	v_mfma_f32_16x16x32_bf16 v[112:115], v[180:183], v[188:191], v[112:115]
	v_mfma_f32_16x16x32_bf16 v[96:99], v[180:183], v[196:199], v[96:99]
	v_mfma_f32_16x16x32_bf16 v[96:99], v[184:187], v[200:203], v[96:99]
	v_mfma_f32_16x16x32_bf16 v[100:103], v[148:151], v[200:203], v[100:103]
	v_mfma_f32_16x16x32_bf16 v[100:103], v[144:147], v[196:199], v[100:103]
	v_mfma_f32_16x16x32_bf16 v[104:107], v[136:139], v[196:199], v[104:107]
	v_mfma_f32_16x16x32_bf16 v[104:107], v[140:143], v[200:203], v[104:107]
	v_mfma_f32_16x16x32_bf16 v[108:111], v[132:135], v[200:203], v[108:111]
	v_mfma_f32_16x16x32_bf16 v[108:111], v[128:131], v[196:199], v[108:111]
	v_mfma_f32_16x16x32_bf16 v[92:95], v[128:131], v[204:207], v[92:95]
	v_mfma_f32_16x16x32_bf16 v[92:95], v[132:135], v[208:211], v[92:95]
	v_mfma_f32_16x16x32_bf16 v[88:91], v[140:143], v[208:211], v[88:91]
	v_mfma_f32_16x16x32_bf16 v[88:91], v[136:139], v[204:207], v[88:91]
	v_mfma_f32_16x16x32_bf16 v[84:87], v[144:147], v[204:207], v[84:87]
	v_mfma_f32_16x16x32_bf16 v[84:87], v[148:151], v[208:211], v[84:87]
	v_mfma_f32_16x16x32_bf16 v[80:83], v[184:187], v[208:211], v[80:83]
	v_mfma_f32_16x16x32_bf16 v[80:83], v[180:183], v[204:207], v[80:83]
	v_mfma_f32_16x16x32_bf16 v[64:67], v[180:183], v[212:215], v[64:67]
	v_mfma_f32_16x16x32_bf16 v[64:67], v[184:187], v[216:219], v[64:67]
	v_mfma_f32_16x16x32_bf16 v[68:71], v[148:151], v[216:219], v[68:71]
	v_mfma_f32_16x16x32_bf16 v[68:71], v[144:147], v[212:215], v[68:71]
	v_mfma_f32_16x16x32_bf16 v[72:75], v[136:139], v[212:215], v[72:75]
	v_mfma_f32_16x16x32_bf16 v[72:75], v[140:143], v[216:219], v[72:75]
	v_mfma_f32_16x16x32_bf16 v[76:79], v[132:135], v[216:219], v[76:79]
	v_mfma_f32_16x16x32_bf16 v[76:79], v[128:131], v[212:215], v[76:79]
	s_barrier
	s_add_i32 s34, s41, s33
	v_lshl_add_u64 v[172:173], v[172:173], 0, s[16:17]
	s_mov_b32 m0, s34
	s_nop 0
	global_load_lds_dwordx4 v[172:173], off
	s_add_i32 m0, s34, 0x2000
	s_add_u32 s30, s30, 0x100800
	v_lshl_add_u64 v[172:173], v[220:221], 0, s[16:17]
	s_addc_u32 s31, s31, 0
	s_add_i32 s34, s42, s33
	global_load_lds_dwordx4 v[172:173], off
	v_lshl_add_u64 v[172:173], s[30:31], 0, v[154:155]
	s_mov_b32 m0, s34
	s_nop 0
	global_load_lds_dwordx4 v[172:173], off
	v_lshl_add_u64 v[172:173], s[30:31], 0, v[158:159]
	s_add_i32 m0, s34, 0x2000
	s_nop 0
	global_load_lds_dwordx4 v[172:173], off
	v_lshl_add_u64 v[172:173], v[222:223], 0, s[18:19]
	s_mov_b32 m0, s63
	s_nop 0
	global_load_lds_dwordx4 v[172:173], off
	v_lshl_add_u64 v[172:173], v[224:225], 0, s[18:19]
	s_mov_b32 m0, s64
	s_nop 0
	global_load_lds_dwordx4 v[172:173], off
	ds_read_b128 v[188:191], v178 offset:49152
	ds_read_b128 v[192:195], v178 offset:50176
	ds_read_b128 v[196:199], v178 offset:51200
	ds_read_b128 v[200:203], v178 offset:52224
	ds_read_b128 v[204:207], v178 offset:53248
	ds_read_b128 v[208:211], v178 offset:54272
	ds_read_b128 v[212:215], v178 offset:55296
	ds_read_b128 v[216:219], v178 offset:56320
	s_waitcnt vmcnt(8)
	s_waitcnt lgkmcnt(0)
	s_barrier
	s_waitcnt lgkmcnt(0)
	v_mfma_f32_16x16x32_bf16 v[60:63], v[128:131], v[188:191], v[60:63]
	v_mfma_f32_16x16x32_bf16 v[60:63], v[132:135], v[192:195], v[60:63]
	v_mfma_f32_16x16x32_bf16 v[56:59], v[140:143], v[192:195], v[56:59]
	v_mfma_f32_16x16x32_bf16 v[56:59], v[136:139], v[188:191], v[56:59]
	v_mfma_f32_16x16x32_bf16 v[52:55], v[144:147], v[188:191], v[52:55]
	v_mfma_f32_16x16x32_bf16 v[52:55], v[148:151], v[192:195], v[52:55]
	v_mfma_f32_16x16x32_bf16 v[48:51], v[184:187], v[192:195], v[48:51]
	v_mfma_f32_16x16x32_bf16 v[48:51], v[180:183], v[188:191], v[48:51]
	v_mfma_f32_16x16x32_bf16 v[32:35], v[180:183], v[196:199], v[32:35]
	v_mfma_f32_16x16x32_bf16 v[32:35], v[184:187], v[200:203], v[32:35]
	v_mfma_f32_16x16x32_bf16 v[36:39], v[148:151], v[200:203], v[36:39]
	v_mfma_f32_16x16x32_bf16 v[36:39], v[144:147], v[196:199], v[36:39]
	v_mfma_f32_16x16x32_bf16 v[40:43], v[136:139], v[196:199], v[40:43]
	v_mfma_f32_16x16x32_bf16 v[40:43], v[140:143], v[200:203], v[40:43]
	v_mfma_f32_16x16x32_bf16 v[44:47], v[132:135], v[200:203], v[44:47]
	v_mfma_f32_16x16x32_bf16 v[44:47], v[128:131], v[196:199], v[44:47]
	v_mfma_f32_16x16x32_bf16 v[28:31], v[128:131], v[204:207], v[28:31]
	v_mfma_f32_16x16x32_bf16 v[28:31], v[132:135], v[208:211], v[28:31]
	v_mfma_f32_16x16x32_bf16 v[24:27], v[140:143], v[208:211], v[24:27]
	v_mfma_f32_16x16x32_bf16 v[24:27], v[136:139], v[204:207], v[24:27]
	v_mfma_f32_16x16x32_bf16 v[20:23], v[144:147], v[204:207], v[20:23]
	v_mfma_f32_16x16x32_bf16 v[20:23], v[148:151], v[208:211], v[20:23]
	v_mfma_f32_16x16x32_bf16 v[16:19], v[184:187], v[208:211], v[16:19]
	v_mfma_f32_16x16x32_bf16 v[16:19], v[180:183], v[204:207], v[16:19]
	v_mfma_f32_16x16x32_bf16 v[0:3], v[180:183], v[212:215], v[0:3]
	v_mfma_f32_16x16x32_bf16 v[0:3], v[184:187], v[216:219], v[0:3]
	v_mfma_f32_16x16x32_bf16 v[4:7], v[148:151], v[216:219], v[4:7]
	v_mfma_f32_16x16x32_bf16 v[4:7], v[144:147], v[212:215], v[4:7]
	v_mfma_f32_16x16x32_bf16 v[8:11], v[136:139], v[212:215], v[8:11]
	v_mfma_f32_16x16x32_bf16 v[8:11], v[140:143], v[216:219], v[8:11]
	v_mfma_f32_16x16x32_bf16 v[12:15], v[132:135], v[216:219], v[12:15]
	v_mfma_f32_16x16x32_bf16 v[12:15], v[128:131], v[212:215], v[12:15]
	s_barrier
	s_add_i32 s40, s40, 2
	s_add_u32 s38, s38, 0x1000
	s_addc_u32 s39, s39, 0
	s_add_u32 s28, s28, 0x100
	s_addc_u32 s29, s29, 0
	s_cmp_gt_u32 s40, 61
	s_cbranch_scc0 .LBB0_1202
	s_and_b64 vcc, exec, s[10:11]
	s_cbranch_vccz .LBB0_1205
	s_barrier

.LBB0_1263:
	ds_read_b128 v[146:149], v152
	ds_read_b128 v[156:159], v152 offset:1024
	ds_read_b128 v[160:163], v152 offset:2048
	ds_read_b128 v[164:167], v152 offset:3072
	ds_read_b128 v[168:171], v153
	ds_read_b128 v[172:175], v153 offset:1024
	ds_read_b128 v[176:179], v153 offset:2048
	ds_read_b128 v[180:183], v153 offset:3072
	s_add_u32 s22, s20, 0x100
	s_addc_u32 s23, s21, 0
	s_cmp_eq_u32 s46, 12
	s_cselect_b32 s27, s5, s23
	s_cselect_b32 s26, s4, s22
	s_cselect_b32 s25, s19, s15
	s_cselect_b32 s24, s18, s6
	v_lshl_add_u64 v[184:185], s[20:21], 0, v[136:137]
	s_add_i32 m0, s17, 0xc000
	s_nop 0
	global_load_lds_dwordx4 v[184:185], off
	v_lshl_add_u64 v[184:185], s[20:21], 0, v[138:139]
	s_add_i32 m0, s17, 0xe000
	s_nop 0
	global_load_lds_dwordx4 v[184:185], off
	ds_read_b128 v[184:187], v154
	ds_read_b128 v[188:191], v154 offset:1024
	ds_read_b128 v[192:195], v154 offset:2048
	ds_read_b128 v[196:199], v154 offset:3072
	ds_read_b128 v[200:203], v154 offset:4096
	ds_read_b128 v[204:207], v154 offset:5120
	ds_read_b128 v[208:211], v154 offset:6144
	ds_read_b128 v[212:215], v154 offset:7168
	s_waitcnt vmcnt(8)
	s_waitcnt lgkmcnt(0)
	s_barrier
	s_waitcnt lgkmcnt(0)
	v_mfma_f32_16x16x32_bf16 v[124:127], v[146:149], v[184:187], v[124:127]
	v_mfma_f32_16x16x32_bf16 v[124:127], v[156:159], v[188:191], v[124:127]
	v_mfma_f32_16x16x32_bf16 v[120:123], v[164:167], v[188:191], v[120:123]
	v_mfma_f32_16x16x32_bf16 v[120:123], v[160:163], v[184:187], v[120:123]
	v_mfma_f32_16x16x32_bf16 v[116:119], v[168:171], v[184:187], v[116:119]
	v_mfma_f32_16x16x32_bf16 v[116:119], v[172:175], v[188:191], v[116:119]
	v_mfma_f32_16x16x32_bf16 v[108:111], v[180:183], v[188:191], v[108:111]
	v_mfma_f32_16x16x32_bf16 v[108:111], v[176:179], v[184:187], v[108:111]
	v_mfma_f32_16x16x32_bf16 v[92:95], v[176:179], v[192:195], v[92:95]
	v_mfma_f32_16x16x32_bf16 v[92:95], v[180:183], v[196:199], v[92:95]
	v_mfma_f32_16x16x32_bf16 v[100:103], v[172:175], v[196:199], v[100:103]
	v_mfma_f32_16x16x32_bf16 v[100:103], v[168:171], v[192:195], v[100:103]
	v_mfma_f32_16x16x32_bf16 v[104:107], v[160:163], v[192:195], v[104:107]
	v_mfma_f32_16x16x32_bf16 v[104:107], v[164:167], v[196:199], v[104:107]
	v_mfma_f32_16x16x32_bf16 v[112:115], v[156:159], v[196:199], v[112:115]
	v_mfma_f32_16x16x32_bf16 v[112:115], v[146:149], v[192:195], v[112:115]
	v_mfma_f32_16x16x32_bf16 v[96:99], v[146:149], v[200:203], v[96:99]
	v_mfma_f32_16x16x32_bf16 v[96:99], v[156:159], v[204:207], v[96:99]
	v_mfma_f32_16x16x32_bf16 v[88:91], v[164:167], v[204:207], v[88:91]
	v_mfma_f32_16x16x32_bf16 v[88:91], v[160:163], v[200:203], v[88:91]
	v_mfma_f32_16x16x32_bf16 v[84:87], v[168:171], v[200:203], v[84:87]
	v_mfma_f32_16x16x32_bf16 v[84:87], v[172:175], v[204:207], v[84:87]
	v_mfma_f32_16x16x32_bf16 v[76:79], v[180:183], v[204:207], v[76:79]
	v_mfma_f32_16x16x32_bf16 v[76:79], v[176:179], v[200:203], v[76:79]
	v_mfma_f32_16x16x32_bf16 v[64:67], v[176:179], v[208:211], v[64:67]
	v_mfma_f32_16x16x32_bf16 v[64:67], v[180:183], v[212:215], v[64:67]
	v_mfma_f32_16x16x32_bf16 v[68:71], v[172:175], v[212:215], v[68:71]
	v_mfma_f32_16x16x32_bf16 v[68:71], v[168:171], v[208:211], v[68:71]
	v_mfma_f32_16x16x32_bf16 v[72:75], v[160:163], v[208:211], v[72:75]
	v_mfma_f32_16x16x32_bf16 v[72:75], v[164:167], v[212:215], v[72:75]
	v_mfma_f32_16x16x32_bf16 v[80:83], v[156:159], v[212:215], v[80:83]
	v_mfma_f32_16x16x32_bf16 v[80:83], v[146:149], v[208:211], v[80:83]
	s_barrier
	s_add_i32 s20, s41, s33
	v_lshl_add_u64 v[216:217], s[24:25], 0, v[130:131]
	s_mov_b32 m0, s20
	v_lshl_add_u64 v[218:219], s[24:25], 0, v[134:135]
	global_load_lds_dwordx4 v[216:217], off
	s_add_i32 m0, s20, 0x2000
	s_add_u32 s20, s24, 0x200000
	s_addc_u32 s21, s25, 0
	s_add_i32 s47, s42, s33
	global_load_lds_dwordx4 v[218:219], off
	v_lshl_add_u64 v[184:185], s[20:21], 0, v[130:131]
	s_mov_b32 m0, s47
	v_lshl_add_u64 v[220:221], s[26:27], 0, v[128:129]
	global_load_lds_dwordx4 v[184:185], off
	v_lshl_add_u64 v[184:185], s[20:21], 0, v[134:135]
	s_add_i32 m0, s47, 0x2000
	v_lshl_add_u64 v[222:223], s[26:27], 0, v[132:133]
	global_load_lds_dwordx4 v[184:185], off
	s_mov_b32 m0, s17
	s_nop 0
	global_load_lds_dwordx4 v[220:221], off
	s_mov_b32 m0, s34
	s_nop 0
	global_load_lds_dwordx4 v[222:223], off
	ds_read_b128 v[184:187], v154 offset:16384
	ds_read_b128 v[188:191], v154 offset:17408
	ds_read_b128 v[192:195], v154 offset:18432
	ds_read_b128 v[196:199], v154 offset:19456
	ds_read_b128 v[200:203], v154 offset:20480
	ds_read_b128 v[204:207], v154 offset:21504
	ds_read_b128 v[208:211], v154 offset:22528
	ds_read_b128 v[212:215], v154 offset:23552
	s_waitcnt vmcnt(8)
	s_waitcnt lgkmcnt(0)
	s_barrier
	s_waitcnt lgkmcnt(0)
	v_mfma_f32_16x16x32_bf16 v[60:63], v[146:149], v[184:187], v[60:63]
	v_mfma_f32_16x16x32_bf16 v[60:63], v[156:159], v[188:191], v[60:63]
	v_mfma_f32_16x16x32_bf16 v[56:59], v[164:167], v[188:191], v[56:59]
	v_mfma_f32_16x16x32_bf16 v[56:59], v[160:163], v[184:187], v[56:59]
	v_mfma_f32_16x16x32_bf16 v[52:55], v[168:171], v[184:187], v[52:55]
	v_mfma_f32_16x16x32_bf16 v[52:55], v[172:175], v[188:191], v[52:55]
	v_mfma_f32_16x16x32_bf16 v[44:47], v[180:183], v[188:191], v[44:47]
	v_mfma_f32_16x16x32_bf16 v[44:47], v[176:179], v[184:187], v[44:47]
	v_mfma_f32_16x16x32_bf16 v[28:31], v[176:179], v[192:195], v[28:31]
	v_mfma_f32_16x16x32_bf16 v[28:31], v[180:183], v[196:199], v[28:31]
	v_mfma_f32_16x16x32_bf16 v[36:39], v[172:175], v[196:199], v[36:39]
	v_mfma_f32_16x16x32_bf16 v[36:39], v[168:171], v[192:195], v[36:39]
	v_mfma_f32_16x16x32_bf16 v[40:43], v[160:163], v[192:195], v[40:43]
	v_mfma_f32_16x16x32_bf16 v[40:43], v[164:167], v[196:199], v[40:43]
	v_mfma_f32_16x16x32_bf16 v[48:51], v[156:159], v[196:199], v[48:51]
	v_mfma_f32_16x16x32_bf16 v[48:51], v[146:149], v[192:195], v[48:51]
	v_mfma_f32_16x16x32_bf16 v[32:35], v[146:149], v[200:203], v[32:35]
	v_mfma_f32_16x16x32_bf16 v[32:35], v[156:159], v[204:207], v[32:35]
	v_mfma_f32_16x16x32_bf16 v[24:27], v[164:167], v[204:207], v[24:27]
	v_mfma_f32_16x16x32_bf16 v[24:27], v[160:163], v[200:203], v[24:27]
	v_mfma_f32_16x16x32_bf16 v[20:23], v[168:171], v[200:203], v[20:23]
	v_mfma_f32_16x16x32_bf16 v[20:23], v[172:175], v[204:207], v[20:23]
	v_mfma_f32_16x16x32_bf16 v[12:15], v[180:183], v[204:207], v[12:15]
	v_mfma_f32_16x16x32_bf16 v[12:15], v[176:179], v[200:203], v[12:15]
	v_mfma_f32_16x16x32_bf16 v[0:3], v[176:179], v[208:211], v[0:3]
	v_mfma_f32_16x16x32_bf16 v[0:3], v[180:183], v[212:215], v[0:3]
	v_mfma_f32_16x16x32_bf16 v[4:7], v[172:175], v[212:215], v[4:7]
	v_mfma_f32_16x16x32_bf16 v[4:7], v[168:171], v[208:211], v[4:7]
	v_mfma_f32_16x16x32_bf16 v[8:11], v[160:163], v[208:211], v[8:11]
	v_mfma_f32_16x16x32_bf16 v[8:11], v[164:167], v[212:215], v[8:11]
	v_mfma_f32_16x16x32_bf16 v[16:19], v[156:159], v[212:215], v[16:19]
	v_mfma_f32_16x16x32_bf16 v[16:19], v[146:149], v[208:211], v[16:19]
	s_barrier
	s_add_i32 s47, 0, 0x18000
	v_add_u32_e32 v144, s47, v145
	s_add_i32 s48, 0, 0x1c000
	ds_read_b128 v[146:149], v144
	ds_read_b128 v[156:159], v144 offset:1024
	ds_read_b128 v[160:163], v144 offset:2048
	ds_read_b128 v[164:167], v144 offset:3072
	v_add_u32_e32 v144, s48, v145
	ds_read_b128 v[168:171], v144
	ds_read_b128 v[172:175], v144 offset:1024
	ds_read_b128 v[176:179], v144 offset:2048
	ds_read_b128 v[180:183], v144 offset:3072
	s_add_u32 s20, s26, 0x200000
	s_addc_u32 s21, s27, 0
	s_mov_b32 m0, s35
	v_lshl_add_u64 v[184:185], s[20:21], 0, v[128:129]
	global_load_lds_dwordx4 v[184:185], off
	v_lshl_add_u64 v[184:185], s[20:21], 0, v[132:133]
	s_mov_b32 m0, s36
	s_nop 0
	global_load_lds_dwordx4 v[184:185], off
	ds_read_b128 v[184:187], v154 offset:32768
	ds_read_b128 v[188:191], v154 offset:33792
	ds_read_b128 v[192:195], v154 offset:34816
	ds_read_b128 v[196:199], v154 offset:35840
	ds_read_b128 v[200:203], v154 offset:36864
	ds_read_b128 v[204:207], v154 offset:37888
	ds_read_b128 v[208:211], v154 offset:38912
	ds_read_b128 v[212:215], v154 offset:39936
	s_waitcnt vmcnt(8)
	s_waitcnt lgkmcnt(0)
	s_barrier
	s_waitcnt lgkmcnt(0)
	v_mfma_f32_16x16x32_bf16 v[124:127], v[146:149], v[184:187], v[124:127]
	v_mfma_f32_16x16x32_bf16 v[124:127], v[156:159], v[188:191], v[124:127]
	v_mfma_f32_16x16x32_bf16 v[120:123], v[164:167], v[188:191], v[120:123]
	v_mfma_f32_16x16x32_bf16 v[120:123], v[160:163], v[184:187], v[120:123]
	v_mfma_f32_16x16x32_bf16 v[116:119], v[168:171], v[184:187], v[116:119]
	v_mfma_f32_16x16x32_bf16 v[116:119], v[172:175], v[188:191], v[116:119]
	v_mfma_f32_16x16x32_bf16 v[108:111], v[180:183], v[188:191], v[108:111]
	v_mfma_f32_16x16x32_bf16 v[108:111], v[176:179], v[184:187], v[108:111]
	v_mfma_f32_16x16x32_bf16 v[92:95], v[176:179], v[192:195], v[92:95]
	v_mfma_f32_16x16x32_bf16 v[92:95], v[180:183], v[196:199], v[92:95]
	v_mfma_f32_16x16x32_bf16 v[100:103], v[172:175], v[196:199], v[100:103]
	v_mfma_f32_16x16x32_bf16 v[100:103], v[168:171], v[192:195], v[100:103]
	v_mfma_f32_16x16x32_bf16 v[104:107], v[160:163], v[192:195], v[104:107]
	v_mfma_f32_16x16x32_bf16 v[104:107], v[164:167], v[196:199], v[104:107]
	v_mfma_f32_16x16x32_bf16 v[112:115], v[156:159], v[196:199], v[112:115]
	v_mfma_f32_16x16x32_bf16 v[112:115], v[146:149], v[192:195], v[112:115]
	v_mfma_f32_16x16x32_bf16 v[96:99], v[146:149], v[200:203], v[96:99]
	v_mfma_f32_16x16x32_bf16 v[96:99], v[156:159], v[204:207], v[96:99]
	v_mfma_f32_16x16x32_bf16 v[88:91], v[164:167], v[204:207], v[88:91]
	v_mfma_f32_16x16x32_bf16 v[88:91], v[160:163], v[200:203], v[88:91]
	v_mfma_f32_16x16x32_bf16 v[84:87], v[168:171], v[200:203], v[84:87]
	v_mfma_f32_16x16x32_bf16 v[84:87], v[172:175], v[204:207], v[84:87]
	v_mfma_f32_16x16x32_bf16 v[76:79], v[180:183], v[204:207], v[76:79]
	v_mfma_f32_16x16x32_bf16 v[76:79], v[176:179], v[200:203], v[76:79]
	v_mfma_f32_16x16x32_bf16 v[64:67], v[176:179], v[208:211], v[64:67]
	v_mfma_f32_16x16x32_bf16 v[64:67], v[180:183], v[212:215], v[64:67]
	v_mfma_f32_16x16x32_bf16 v[68:71], v[172:175], v[212:215], v[68:71]
	v_mfma_f32_16x16x32_bf16 v[68:71], v[168:171], v[208:211], v[68:71]
	v_mfma_f32_16x16x32_bf16 v[72:75], v[160:163], v[208:211], v[72:75]
	v_mfma_f32_16x16x32_bf16 v[72:75], v[164:167], v[212:215], v[72:75]
	v_mfma_f32_16x16x32_bf16 v[80:83], v[156:159], v[212:215], v[80:83]
	v_mfma_f32_16x16x32_bf16 v[80:83], v[146:149], v[208:211], v[80:83]
	s_barrier
	s_add_i32 s20, s47, s33
	v_lshl_add_u64 v[184:185], v[216:217], 0, s[12:13]
	s_mov_b32 m0, s20
	s_nop 0
	global_load_lds_dwordx4 v[184:185], off
	s_add_i32 m0, s20, 0x2000
	s_add_u32 s20, s24, 0x200080
	v_lshl_add_u64 v[184:185], v[218:219], 0, s[12:13]
	s_addc_u32 s21, s25, 0
	s_add_i32 s24, s48, s33
	global_load_lds_dwordx4 v[184:185], off
	v_lshl_add_u64 v[184:185], s[20:21], 0, v[130:131]
	s_mov_b32 m0, s24
	s_nop 0
	global_load_lds_dwordx4 v[184:185], off
	v_lshl_add_u64 v[184:185], s[20:21], 0, v[134:135]
	s_add_i32 m0, s24, 0x2000
	s_nop 0
	global_load_lds_dwordx4 v[184:185], off
	v_lshl_add_u64 v[184:185], v[220:221], 0, s[12:13]
	s_mov_b32 m0, s37
	s_nop 0
	global_load_lds_dwordx4 v[184:185], off
	v_lshl_add_u64 v[184:185], v[222:223], 0, s[12:13]
	s_mov_b32 m0, s38
	s_nop 0
	global_load_lds_dwordx4 v[184:185], off
	ds_read_b128 v[184:187], v154 offset:49152
	ds_read_b128 v[188:191], v154 offset:50176
	ds_read_b128 v[192:195], v154 offset:51200
	ds_read_b128 v[196:199], v154 offset:52224
	ds_read_b128 v[200:203], v154 offset:53248
	ds_read_b128 v[204:207], v154 offset:54272
	ds_read_b128 v[208:211], v154 offset:55296
	ds_read_b128 v[212:215], v154 offset:56320
	s_waitcnt vmcnt(8)
	s_waitcnt lgkmcnt(0)
	s_barrier
	s_waitcnt lgkmcnt(0)
	v_mfma_f32_16x16x32_bf16 v[60:63], v[146:149], v[184:187], v[60:63]
	v_mfma_f32_16x16x32_bf16 v[60:63], v[156:159], v[188:191], v[60:63]
	v_mfma_f32_16x16x32_bf16 v[56:59], v[164:167], v[188:191], v[56:59]
	v_mfma_f32_16x16x32_bf16 v[56:59], v[160:163], v[184:187], v[56:59]
	v_mfma_f32_16x16x32_bf16 v[52:55], v[168:171], v[184:187], v[52:55]
	v_mfma_f32_16x16x32_bf16 v[52:55], v[172:175], v[188:191], v[52:55]
	v_mfma_f32_16x16x32_bf16 v[44:47], v[180:183], v[188:191], v[44:47]
	v_mfma_f32_16x16x32_bf16 v[44:47], v[176:179], v[184:187], v[44:47]
	v_mfma_f32_16x16x32_bf16 v[28:31], v[176:179], v[192:195], v[28:31]
	v_mfma_f32_16x16x32_bf16 v[28:31], v[180:183], v[196:199], v[28:31]
	v_mfma_f32_16x16x32_bf16 v[36:39], v[172:175], v[196:199], v[36:39]
	v_mfma_f32_16x16x32_bf16 v[36:39], v[168:171], v[192:195], v[36:39]
	v_mfma_f32_16x16x32_bf16 v[40:43], v[160:163], v[192:195], v[40:43]
	v_mfma_f32_16x16x32_bf16 v[40:43], v[164:167], v[196:199], v[40:43]
	v_mfma_f32_16x16x32_bf16 v[48:51], v[156:159], v[196:199], v[48:51]
	v_mfma_f32_16x16x32_bf16 v[48:51], v[146:149], v[192:195], v[48:51]
	v_mfma_f32_16x16x32_bf16 v[32:35], v[146:149], v[200:203], v[32:35]
	v_mfma_f32_16x16x32_bf16 v[32:35], v[156:159], v[204:207], v[32:35]
	v_mfma_f32_16x16x32_bf16 v[24:27], v[164:167], v[204:207], v[24:27]
	v_mfma_f32_16x16x32_bf16 v[24:27], v[160:163], v[200:203], v[24:27]
	v_mfma_f32_16x16x32_bf16 v[20:23], v[168:171], v[200:203], v[20:23]
	v_mfma_f32_16x16x32_bf16 v[20:23], v[172:175], v[204:207], v[20:23]
	v_mfma_f32_16x16x32_bf16 v[12:15], v[180:183], v[204:207], v[12:15]
	v_mfma_f32_16x16x32_bf16 v[12:15], v[176:179], v[200:203], v[12:15]
	v_mfma_f32_16x16x32_bf16 v[0:3], v[176:179], v[208:211], v[0:3]
	v_mfma_f32_16x16x32_bf16 v[0:3], v[180:183], v[212:215], v[0:3]
	v_mfma_f32_16x16x32_bf16 v[4:7], v[172:175], v[212:215], v[4:7]
	v_mfma_f32_16x16x32_bf16 v[4:7], v[168:171], v[208:211], v[4:7]
	v_mfma_f32_16x16x32_bf16 v[8:11], v[160:163], v[208:211], v[8:11]
	v_mfma_f32_16x16x32_bf16 v[8:11], v[164:167], v[212:215], v[8:11]
	v_mfma_f32_16x16x32_bf16 v[16:19], v[156:159], v[212:215], v[16:19]
	v_mfma_f32_16x16x32_bf16 v[16:19], v[146:149], v[208:211], v[16:19]
	s_barrier
	s_add_i32 s46, s46, 2
	s_add_u32 s6, s6, 0x100
	s_addc_u32 s15, s15, 0
	s_cmp_gt_u32 s46, 13
	s_mov_b64 s[20:21], s[22:23]
	s_cbranch_scc0 .LBB0_1263
	s_and_b64 vcc, exec, s[8:9]
	s_cbranch_vccz .LBB0_1266
	s_barrier

.LBB0_1340:
	v_add_u32_e32 v166, s51, v152
	v_add_u32_e32 v182, s52, v152
	ds_read_b128 v[154:157], v166
	ds_read_b128 v[158:161], v166 offset:1024
	ds_read_b128 v[162:165], v166 offset:2048
	ds_read_b128 v[166:169], v166 offset:3072
	ds_read_b128 v[170:173], v182
	ds_read_b128 v[174:177], v182 offset:1024
	ds_read_b128 v[178:181], v182 offset:2048
	ds_read_b128 v[182:185], v182 offset:3072
	s_add_u32 s30, s10, s28
	s_addc_u32 s31, s11, s29
	s_cmp_eq_u32 s58, 60
	s_cselect_b32 s35, s23, s31
	s_cselect_b32 s34, s54, s30
	s_cselect_b32 s31, s21, s57
	s_cselect_b32 s30, s55, s56
	v_lshl_add_u64 v[186:187], s[10:11], 0, v[146:147]
	s_add_i32 m0, s44, 0xc000
	s_nop 0
	global_load_lds_dwordx4 v[186:187], off
	v_lshl_add_u64 v[186:187], s[10:11], 0, v[144:145]
	s_add_i32 m0, s44, 0xe000
	s_nop 0
	global_load_lds_dwordx4 v[186:187], off
	ds_read_b128 v[186:189], v153
	ds_read_b128 v[190:193], v153 offset:1024
	ds_read_b128 v[194:197], v153 offset:2048
	ds_read_b128 v[198:201], v153 offset:3072
	ds_read_b128 v[202:205], v153 offset:4096
	ds_read_b128 v[206:209], v153 offset:5120
	ds_read_b128 v[210:213], v153 offset:6144
	ds_read_b128 v[214:217], v153 offset:7168
	s_waitcnt vmcnt(8)
	s_waitcnt lgkmcnt(0)
	s_barrier
	s_waitcnt lgkmcnt(0)
	v_mfma_f32_16x16x32_bf16 v[124:127], v[154:157], v[186:189], v[124:127]
	v_mfma_f32_16x16x32_bf16 v[124:127], v[158:161], v[190:193], v[124:127]
	v_mfma_f32_16x16x32_bf16 v[120:123], v[166:169], v[190:193], v[120:123]
	v_mfma_f32_16x16x32_bf16 v[120:123], v[162:165], v[186:189], v[120:123]
	v_mfma_f32_16x16x32_bf16 v[116:119], v[170:173], v[186:189], v[116:119]
	v_mfma_f32_16x16x32_bf16 v[116:119], v[174:177], v[190:193], v[116:119]
	v_mfma_f32_16x16x32_bf16 v[112:115], v[182:185], v[190:193], v[112:115]
	v_mfma_f32_16x16x32_bf16 v[112:115], v[178:181], v[186:189], v[112:115]
	v_mfma_f32_16x16x32_bf16 v[96:99], v[178:181], v[194:197], v[96:99]
	v_mfma_f32_16x16x32_bf16 v[96:99], v[182:185], v[198:201], v[96:99]
	v_mfma_f32_16x16x32_bf16 v[100:103], v[174:177], v[198:201], v[100:103]
	v_mfma_f32_16x16x32_bf16 v[100:103], v[170:173], v[194:197], v[100:103]
	v_mfma_f32_16x16x32_bf16 v[104:107], v[162:165], v[194:197], v[104:107]
	v_mfma_f32_16x16x32_bf16 v[104:107], v[166:169], v[198:201], v[104:107]
	v_mfma_f32_16x16x32_bf16 v[108:111], v[158:161], v[198:201], v[108:111]
	v_mfma_f32_16x16x32_bf16 v[108:111], v[154:157], v[194:197], v[108:111]
	v_mfma_f32_16x16x32_bf16 v[92:95], v[154:157], v[202:205], v[92:95]
	v_mfma_f32_16x16x32_bf16 v[92:95], v[158:161], v[206:209], v[92:95]
	v_mfma_f32_16x16x32_bf16 v[88:91], v[166:169], v[206:209], v[88:91]
	v_mfma_f32_16x16x32_bf16 v[88:91], v[162:165], v[202:205], v[88:91]
	v_mfma_f32_16x16x32_bf16 v[84:87], v[170:173], v[202:205], v[84:87]
	v_mfma_f32_16x16x32_bf16 v[84:87], v[174:177], v[206:209], v[84:87]
	v_mfma_f32_16x16x32_bf16 v[80:83], v[182:185], v[206:209], v[80:83]
	v_mfma_f32_16x16x32_bf16 v[80:83], v[178:181], v[202:205], v[80:83]
	v_mfma_f32_16x16x32_bf16 v[64:67], v[178:181], v[210:213], v[64:67]
	v_mfma_f32_16x16x32_bf16 v[64:67], v[182:185], v[214:217], v[64:67]
	v_mfma_f32_16x16x32_bf16 v[68:71], v[174:177], v[214:217], v[68:71]
	v_mfma_f32_16x16x32_bf16 v[68:71], v[170:173], v[210:213], v[68:71]
	v_mfma_f32_16x16x32_bf16 v[72:75], v[162:165], v[210:213], v[72:75]
	v_mfma_f32_16x16x32_bf16 v[72:75], v[166:169], v[214:217], v[72:75]
	v_mfma_f32_16x16x32_bf16 v[76:79], v[158:161], v[214:217], v[76:79]
	v_mfma_f32_16x16x32_bf16 v[76:79], v[154:157], v[210:213], v[76:79]
	s_barrier
	s_add_i32 s59, s51, s43
	v_lshl_add_u64 v[218:219], s[30:31], 0, v[130:131]
	s_mov_b32 m0, s59
	v_lshl_add_u64 v[220:221], s[30:31], 0, v[134:135]
	global_load_lds_dwordx4 v[218:219], off
	s_add_i32 m0, s59, 0x2000
	s_add_u32 s60, s30, 0x100000
	s_addc_u32 s61, s31, 0
	s_add_i32 s59, s52, s43
	global_load_lds_dwordx4 v[220:221], off
	v_lshl_add_u64 v[186:187], s[60:61], 0, v[130:131]
	s_mov_b32 m0, s59
	v_lshl_add_u64 v[222:223], s[34:35], 0, v[128:129]
	global_load_lds_dwordx4 v[186:187], off
	v_lshl_add_u64 v[186:187], s[60:61], 0, v[134:135]
	s_add_i32 m0, s59, 0x2000
	v_lshl_add_u64 v[224:225], s[34:35], 0, v[132:133]
	global_load_lds_dwordx4 v[186:187], off
	s_mov_b32 m0, s44
	s_nop 0
	global_load_lds_dwordx4 v[222:223], off
	s_mov_b32 m0, s45
	s_nop 0
	global_load_lds_dwordx4 v[224:225], off
	ds_read_b128 v[186:189], v153 offset:16384
	ds_read_b128 v[190:193], v153 offset:17408
	ds_read_b128 v[194:197], v153 offset:18432
	ds_read_b128 v[198:201], v153 offset:19456
	ds_read_b128 v[202:205], v153 offset:20480
	ds_read_b128 v[206:209], v153 offset:21504
	ds_read_b128 v[210:213], v153 offset:22528
	ds_read_b128 v[214:217], v153 offset:23552
	s_waitcnt vmcnt(8)
	s_waitcnt lgkmcnt(0)
	s_barrier
	s_waitcnt lgkmcnt(0)
	v_mfma_f32_16x16x32_bf16 v[60:63], v[154:157], v[186:189], v[60:63]
	v_mfma_f32_16x16x32_bf16 v[60:63], v[158:161], v[190:193], v[60:63]
	v_mfma_f32_16x16x32_bf16 v[56:59], v[166:169], v[190:193], v[56:59]
	v_mfma_f32_16x16x32_bf16 v[56:59], v[162:165], v[186:189], v[56:59]
	v_mfma_f32_16x16x32_bf16 v[52:55], v[170:173], v[186:189], v[52:55]
	v_mfma_f32_16x16x32_bf16 v[52:55], v[174:177], v[190:193], v[52:55]
	v_mfma_f32_16x16x32_bf16 v[48:51], v[182:185], v[190:193], v[48:51]
	v_mfma_f32_16x16x32_bf16 v[48:51], v[178:181], v[186:189], v[48:51]
	v_mfma_f32_16x16x32_bf16 v[32:35], v[178:181], v[194:197], v[32:35]
	v_mfma_f32_16x16x32_bf16 v[32:35], v[182:185], v[198:201], v[32:35]
	v_mfma_f32_16x16x32_bf16 v[36:39], v[174:177], v[198:201], v[36:39]
	v_mfma_f32_16x16x32_bf16 v[36:39], v[170:173], v[194:197], v[36:39]
	v_mfma_f32_16x16x32_bf16 v[40:43], v[162:165], v[194:197], v[40:43]
	v_mfma_f32_16x16x32_bf16 v[40:43], v[166:169], v[198:201], v[40:43]
	v_mfma_f32_16x16x32_bf16 v[44:47], v[158:161], v[198:201], v[44:47]
	v_mfma_f32_16x16x32_bf16 v[44:47], v[154:157], v[194:197], v[44:47]
	v_mfma_f32_16x16x32_bf16 v[28:31], v[154:157], v[202:205], v[28:31]
	v_mfma_f32_16x16x32_bf16 v[28:31], v[158:161], v[206:209], v[28:31]
	v_mfma_f32_16x16x32_bf16 v[24:27], v[166:169], v[206:209], v[24:27]
	v_mfma_f32_16x16x32_bf16 v[24:27], v[162:165], v[202:205], v[24:27]
	v_mfma_f32_16x16x32_bf16 v[20:23], v[170:173], v[202:205], v[20:23]
	v_mfma_f32_16x16x32_bf16 v[20:23], v[174:177], v[206:209], v[20:23]
	v_mfma_f32_16x16x32_bf16 v[16:19], v[182:185], v[206:209], v[16:19]
	v_mfma_f32_16x16x32_bf16 v[16:19], v[178:181], v[202:205], v[16:19]
	v_mfma_f32_16x16x32_bf16 v[0:3], v[178:181], v[210:213], v[0:3]
	v_mfma_f32_16x16x32_bf16 v[0:3], v[182:185], v[214:217], v[0:3]
	v_mfma_f32_16x16x32_bf16 v[4:7], v[174:177], v[214:217], v[4:7]
	v_mfma_f32_16x16x32_bf16 v[4:7], v[170:173], v[210:213], v[4:7]
	v_mfma_f32_16x16x32_bf16 v[8:11], v[162:165], v[210:213], v[8:11]
	v_mfma_f32_16x16x32_bf16 v[8:11], v[166:169], v[214:217], v[8:11]
	v_mfma_f32_16x16x32_bf16 v[12:15], v[158:161], v[214:217], v[12:15]
	v_mfma_f32_16x16x32_bf16 v[12:15], v[154:157], v[210:213], v[12:15]
	s_barrier
	s_add_i32 s59, 0, 0x18000
	s_add_i32 s60, 0, 0x1c000
	v_add_u32_e32 v166, s59, v152
	v_add_u32_e32 v182, s60, v152
	ds_read_b128 v[154:157], v166
	ds_read_b128 v[158:161], v166 offset:1024
	ds_read_b128 v[162:165], v166 offset:2048
	ds_read_b128 v[166:169], v166 offset:3072
	ds_read_b128 v[170:173], v182
	ds_read_b128 v[174:177], v182 offset:1024
	ds_read_b128 v[178:181], v182 offset:2048
	ds_read_b128 v[182:185], v182 offset:3072
	s_add_u32 s34, s34, 0x100000
	s_addc_u32 s35, s35, 0
	s_mov_b32 m0, s46
	v_lshl_add_u64 v[186:187], s[34:35], 0, v[128:129]
	global_load_lds_dwordx4 v[186:187], off
	v_lshl_add_u64 v[186:187], s[34:35], 0, v[132:133]
	s_mov_b32 m0, s47
	s_nop 0
	global_load_lds_dwordx4 v[186:187], off
	ds_read_b128 v[186:189], v153 offset:32768
	ds_read_b128 v[190:193], v153 offset:33792
	ds_read_b128 v[194:197], v153 offset:34816
	ds_read_b128 v[198:201], v153 offset:35840
	ds_read_b128 v[202:205], v153 offset:36864
	ds_read_b128 v[206:209], v153 offset:37888
	ds_read_b128 v[210:213], v153 offset:38912
	ds_read_b128 v[214:217], v153 offset:39936
	s_waitcnt vmcnt(8)
	s_waitcnt lgkmcnt(0)
	s_barrier
	s_waitcnt lgkmcnt(0)
	v_mfma_f32_16x16x32_bf16 v[124:127], v[154:157], v[186:189], v[124:127]
	v_mfma_f32_16x16x32_bf16 v[124:127], v[158:161], v[190:193], v[124:127]
	v_mfma_f32_16x16x32_bf16 v[120:123], v[166:169], v[190:193], v[120:123]
	v_mfma_f32_16x16x32_bf16 v[120:123], v[162:165], v[186:189], v[120:123]
	v_mfma_f32_16x16x32_bf16 v[116:119], v[170:173], v[186:189], v[116:119]
	v_mfma_f32_16x16x32_bf16 v[116:119], v[174:177], v[190:193], v[116:119]
	v_mfma_f32_16x16x32_bf16 v[112:115], v[182:185], v[190:193], v[112:115]
	v_mfma_f32_16x16x32_bf16 v[112:115], v[178:181], v[186:189], v[112:115]
	v_mfma_f32_16x16x32_bf16 v[96:99], v[178:181], v[194:197], v[96:99]
	v_mfma_f32_16x16x32_bf16 v[96:99], v[182:185], v[198:201], v[96:99]
	v_mfma_f32_16x16x32_bf16 v[100:103], v[174:177], v[198:201], v[100:103]
	v_mfma_f32_16x16x32_bf16 v[100:103], v[170:173], v[194:197], v[100:103]
	v_mfma_f32_16x16x32_bf16 v[104:107], v[162:165], v[194:197], v[104:107]
	v_mfma_f32_16x16x32_bf16 v[104:107], v[166:169], v[198:201], v[104:107]
	v_mfma_f32_16x16x32_bf16 v[108:111], v[158:161], v[198:201], v[108:111]
	v_mfma_f32_16x16x32_bf16 v[108:111], v[154:157], v[194:197], v[108:111]
	v_mfma_f32_16x16x32_bf16 v[92:95], v[154:157], v[202:205], v[92:95]
	v_mfma_f32_16x16x32_bf16 v[92:95], v[158:161], v[206:209], v[92:95]
	v_mfma_f32_16x16x32_bf16 v[88:91], v[166:169], v[206:209], v[88:91]
	v_mfma_f32_16x16x32_bf16 v[88:91], v[162:165], v[202:205], v[88:91]
	v_mfma_f32_16x16x32_bf16 v[84:87], v[170:173], v[202:205], v[84:87]
	v_mfma_f32_16x16x32_bf16 v[84:87], v[174:177], v[206:209], v[84:87]
	v_mfma_f32_16x16x32_bf16 v[80:83], v[182:185], v[206:209], v[80:83]
	v_mfma_f32_16x16x32_bf16 v[80:83], v[178:181], v[202:205], v[80:83]
	v_mfma_f32_16x16x32_bf16 v[64:67], v[178:181], v[210:213], v[64:67]
	v_mfma_f32_16x16x32_bf16 v[64:67], v[182:185], v[214:217], v[64:67]
	v_mfma_f32_16x16x32_bf16 v[68:71], v[174:177], v[214:217], v[68:71]
	v_mfma_f32_16x16x32_bf16 v[68:71], v[170:173], v[210:213], v[68:71]
	v_mfma_f32_16x16x32_bf16 v[72:75], v[162:165], v[210:213], v[72:75]
	v_mfma_f32_16x16x32_bf16 v[72:75], v[166:169], v[214:217], v[72:75]
	v_mfma_f32_16x16x32_bf16 v[76:79], v[158:161], v[214:217], v[76:79]
	v_mfma_f32_16x16x32_bf16 v[76:79], v[154:157], v[210:213], v[76:79]
	s_barrier
	s_add_i32 s34, s59, s43
	v_lshl_add_u64 v[186:187], v[218:219], 0, s[14:15]
	s_mov_b32 m0, s34
	s_nop 0
	global_load_lds_dwordx4 v[186:187], off
	s_add_i32 m0, s34, 0x2000
	s_add_u32 s30, s30, 0x100080
	v_lshl_add_u64 v[186:187], v[220:221], 0, s[14:15]
	s_addc_u32 s31, s31, 0
	s_add_i32 s34, s60, s43
	global_load_lds_dwordx4 v[186:187], off
	v_lshl_add_u64 v[186:187], s[30:31], 0, v[130:131]
	s_mov_b32 m0, s34
	s_nop 0
	global_load_lds_dwordx4 v[186:187], off
	v_lshl_add_u64 v[186:187], s[30:31], 0, v[134:135]
	s_add_i32 m0, s34, 0x2000
	s_nop 0
	global_load_lds_dwordx4 v[186:187], off
	v_lshl_add_u64 v[186:187], v[222:223], 0, s[16:17]
	s_mov_b32 m0, s49
	s_nop 0
	global_load_lds_dwordx4 v[186:187], off
	v_lshl_add_u64 v[186:187], v[224:225], 0, s[16:17]
	s_mov_b32 m0, s50
	s_nop 0
	global_load_lds_dwordx4 v[186:187], off
	ds_read_b128 v[186:189], v153 offset:49152
	ds_read_b128 v[190:193], v153 offset:50176
	ds_read_b128 v[194:197], v153 offset:51200
	ds_read_b128 v[198:201], v153 offset:52224
	ds_read_b128 v[202:205], v153 offset:53248
	ds_read_b128 v[206:209], v153 offset:54272
	ds_read_b128 v[210:213], v153 offset:55296
	ds_read_b128 v[214:217], v153 offset:56320
	s_waitcnt vmcnt(8)
	s_waitcnt lgkmcnt(0)
	s_barrier
	s_waitcnt lgkmcnt(0)
	v_mfma_f32_16x16x32_bf16 v[60:63], v[154:157], v[186:189], v[60:63]
	v_mfma_f32_16x16x32_bf16 v[60:63], v[158:161], v[190:193], v[60:63]
	v_mfma_f32_16x16x32_bf16 v[56:59], v[166:169], v[190:193], v[56:59]
	v_mfma_f32_16x16x32_bf16 v[56:59], v[162:165], v[186:189], v[56:59]
	v_mfma_f32_16x16x32_bf16 v[52:55], v[170:173], v[186:189], v[52:55]
	v_mfma_f32_16x16x32_bf16 v[52:55], v[174:177], v[190:193], v[52:55]
	v_mfma_f32_16x16x32_bf16 v[48:51], v[182:185], v[190:193], v[48:51]
	v_mfma_f32_16x16x32_bf16 v[48:51], v[178:181], v[186:189], v[48:51]
	v_mfma_f32_16x16x32_bf16 v[32:35], v[178:181], v[194:197], v[32:35]
	v_mfma_f32_16x16x32_bf16 v[32:35], v[182:185], v[198:201], v[32:35]
	v_mfma_f32_16x16x32_bf16 v[36:39], v[174:177], v[198:201], v[36:39]
	v_mfma_f32_16x16x32_bf16 v[36:39], v[170:173], v[194:197], v[36:39]
	v_mfma_f32_16x16x32_bf16 v[40:43], v[162:165], v[194:197], v[40:43]
	v_mfma_f32_16x16x32_bf16 v[40:43], v[166:169], v[198:201], v[40:43]
	v_mfma_f32_16x16x32_bf16 v[44:47], v[158:161], v[198:201], v[44:47]
	v_mfma_f32_16x16x32_bf16 v[44:47], v[154:157], v[194:197], v[44:47]
	v_mfma_f32_16x16x32_bf16 v[28:31], v[154:157], v[202:205], v[28:31]
	v_mfma_f32_16x16x32_bf16 v[28:31], v[158:161], v[206:209], v[28:31]
	v_mfma_f32_16x16x32_bf16 v[24:27], v[166:169], v[206:209], v[24:27]
	v_mfma_f32_16x16x32_bf16 v[24:27], v[162:165], v[202:205], v[24:27]
	v_mfma_f32_16x16x32_bf16 v[20:23], v[170:173], v[202:205], v[20:23]
	v_mfma_f32_16x16x32_bf16 v[20:23], v[174:177], v[206:209], v[20:23]
	v_mfma_f32_16x16x32_bf16 v[16:19], v[182:185], v[206:209], v[16:19]
	v_mfma_f32_16x16x32_bf16 v[16:19], v[178:181], v[202:205], v[16:19]
	v_mfma_f32_16x16x32_bf16 v[0:3], v[178:181], v[210:213], v[0:3]
	v_mfma_f32_16x16x32_bf16 v[0:3], v[182:185], v[214:217], v[0:3]
	v_mfma_f32_16x16x32_bf16 v[4:7], v[174:177], v[214:217], v[4:7]
	v_mfma_f32_16x16x32_bf16 v[4:7], v[170:173], v[210:213], v[4:7]
	v_mfma_f32_16x16x32_bf16 v[8:11], v[162:165], v[210:213], v[8:11]
	v_mfma_f32_16x16x32_bf16 v[8:11], v[166:169], v[214:217], v[8:11]
	v_mfma_f32_16x16x32_bf16 v[12:15], v[158:161], v[214:217], v[12:15]
	v_mfma_f32_16x16x32_bf16 v[12:15], v[154:157], v[210:213], v[12:15]
	s_barrier
	s_add_i32 s58, s58, 2
	s_add_u32 s56, s56, 0x100
	s_addc_u32 s57, s57, 0
	s_add_u32 s28, s28, 0x1000
	s_addc_u32 s29, s29, 0
	v_lshl_add_u64 v[146:147], v[146:147], 0, s[18:19]
	s_cmp_gt_u32 s58, 61
	v_lshl_add_u64 v[144:145], v[144:145], 0, s[18:19]
	s_cbranch_scc0 .LBB0_1340
	s_andn2_b64 vcc, exec, s[4:5]
	s_cbranch_vccnz .LBB0_1332
	v_mov_b32_e32 v0, 0
	s_mov_b32 s7, s20
	s_mov_b32 s6, s22
	s_mov_b64 s[8:9], s[26:27]
	s_mov_b64 s[10:11], s[24:25]
	s_mov_b32 s48, s53
	v_mov_b32_e32 v1, v0
	v_mov_b32_e32 v2, v0
	v_mov_b32_e32 v3, v0
	v_mov_b32_e32 v4, v0
	v_mov_b32_e32 v5, v0
	v_mov_b32_e32 v6, v0
	v_mov_b32_e32 v7, v0
	v_mov_b32_e32 v16, v0
	v_mov_b32_e32 v17, v0
	v_mov_b32_e32 v18, v0
	v_mov_b32_e32 v19, v0
	v_mov_b32_e32 v20, v0
	v_mov_b32_e32 v21, v0
	v_mov_b32_e32 v22, v0
	v_mov_b32_e32 v23, v0
	v_mov_b32_e32 v32, v0
	v_mov_b32_e32 v33, v0
	v_mov_b32_e32 v34, v0
	v_mov_b32_e32 v35, v0
	v_mov_b32_e32 v36, v0
	v_mov_b32_e32 v37, v0
	v_mov_b32_e32 v38, v0
	v_mov_b32_e32 v39, v0
	v_mov_b32_e32 v48, v0
	v_mov_b32_e32 v49, v0
	v_mov_b32_e32 v50, v0
	v_mov_b32_e32 v51, v0
	v_mov_b32_e32 v52, v0
	v_mov_b32_e32 v53, v0
	v_mov_b32_e32 v54, v0
	v_mov_b32_e32 v55, v0
	v_mov_b32_e32 v8, v0
	v_mov_b32_e32 v9, v0
	v_mov_b32_e32 v10, v0
	v_mov_b32_e32 v11, v0
	v_mov_b32_e32 v12, v0
	v_mov_b32_e32 v13, v0
	v_mov_b32_e32 v14, v0
	v_mov_b32_e32 v15, v0
	v_mov_b32_e32 v24, v0
	v_mov_b32_e32 v25, v0
	v_mov_b32_e32 v26, v0
	v_mov_b32_e32 v27, v0
	v_mov_b32_e32 v28, v0
	v_mov_b32_e32 v29, v0
	v_mov_b32_e32 v30, v0
	v_mov_b32_e32 v31, v0
	v_mov_b32_e32 v40, v0
	v_mov_b32_e32 v41, v0
	v_mov_b32_e32 v42, v0
	v_mov_b32_e32 v43, v0
	v_mov_b32_e32 v44, v0
	v_mov_b32_e32 v45, v0
	v_mov_b32_e32 v46, v0
	v_mov_b32_e32 v47, v0
	v_mov_b32_e32 v56, v0
	v_mov_b32_e32 v57, v0
	v_mov_b32_e32 v58, v0
	v_mov_b32_e32 v59, v0
	v_mov_b32_e32 v60, v0
	v_mov_b32_e32 v61, v0
	v_mov_b32_e32 v62, v0
	v_mov_b32_e32 v63, v0
	v_mov_b32_e32 v64, v0
	v_mov_b32_e32 v65, v0
	v_mov_b32_e32 v66, v0
	v_mov_b32_e32 v67, v0
	v_mov_b32_e32 v68, v0
	v_mov_b32_e32 v69, v0
	v_mov_b32_e32 v70, v0
	v_mov_b32_e32 v71, v0
	v_mov_b32_e32 v80, v0
	v_mov_b32_e32 v81, v0
	v_mov_b32_e32 v82, v0
	v_mov_b32_e32 v83, v0
	v_mov_b32_e32 v84, v0
	v_mov_b32_e32 v85, v0
	v_mov_b32_e32 v86, v0
	v_mov_b32_e32 v87, v0
	v_mov_b32_e32 v96, v0
	v_mov_b32_e32 v97, v0
	v_mov_b32_e32 v98, v0
	v_mov_b32_e32 v99, v0
	v_mov_b32_e32 v100, v0
	v_mov_b32_e32 v101, v0
	v_mov_b32_e32 v102, v0
	v_mov_b32_e32 v103, v0
	v_mov_b32_e32 v112, v0
	v_mov_b32_e32 v113, v0
	v_mov_b32_e32 v114, v0
	v_mov_b32_e32 v115, v0
	v_mov_b32_e32 v116, v0
	v_mov_b32_e32 v117, v0
	v_mov_b32_e32 v118, v0
	v_mov_b32_e32 v119, v0
	v_mov_b32_e32 v72, v0
	v_mov_b32_e32 v73, v0
	v_mov_b32_e32 v74, v0
	v_mov_b32_e32 v75, v0
	v_mov_b32_e32 v76, v0
	v_mov_b32_e32 v77, v0
	v_mov_b32_e32 v78, v0
	v_mov_b32_e32 v79, v0
	v_mov_b32_e32 v88, v0
	v_mov_b32_e32 v89, v0
	v_mov_b32_e32 v90, v0
	v_mov_b32_e32 v91, v0
	v_mov_b32_e32 v92, v0
	v_mov_b32_e32 v93, v0
	v_mov_b32_e32 v94, v0
	v_mov_b32_e32 v95, v0
	v_mov_b32_e32 v104, v0
	v_mov_b32_e32 v105, v0
	v_mov_b32_e32 v106, v0
	v_mov_b32_e32 v107, v0
	v_mov_b32_e32 v108, v0
	v_mov_b32_e32 v109, v0
	v_mov_b32_e32 v110, v0
	v_mov_b32_e32 v111, v0
	v_mov_b32_e32 v120, v0
	v_mov_b32_e32 v121, v0
	v_mov_b32_e32 v122, v0
	v_mov_b32_e32 v123, v0
	v_mov_b32_e32 v124, v0
	v_mov_b32_e32 v125, v0
	v_mov_b32_e32 v126, v0
	v_mov_b32_e32 v127, v0
	s_branch .LBB0_1332

.LBB0_1435:
	ds_read_b128 v[128:131], v180
	ds_read_b128 v[132:135], v180 offset:1024
	ds_read_b128 v[136:139], v180 offset:2048
	ds_read_b128 v[140:143], v180 offset:3072
	ds_read_b128 v[144:147], v181
	ds_read_b128 v[148:151], v181 offset:1024
	ds_read_b128 v[170:173], v181 offset:2048
	ds_read_b128 v[174:177], v181 offset:3072
	s_add_u32 s26, s24, 0xfffc0080
	s_addc_u32 s27, s25, -1
	s_cmp_eq_u32 s35, 12
	s_cselect_b32 s29, s1, s27
	s_cselect_b32 s28, s19, s26
	s_cselect_b32 s27, s17, s34
	s_cselect_b32 s26, s30, s31
	v_lshl_add_u64 v[184:185], s[24:25], 0, v[162:163]
	s_add_i32 m0, s40, 0xc000
	s_nop 0
	global_load_lds_dwordx4 v[184:185], off
	v_lshl_add_u64 v[184:185], s[24:25], 0, v[164:165]
	s_add_i32 m0, s40, 0xe000
	s_nop 0
	global_load_lds_dwordx4 v[184:185], off
	ds_read_b128 v[184:187], v182
	ds_read_b128 v[188:191], v182 offset:1024
	ds_read_b128 v[192:195], v182 offset:2048
	ds_read_b128 v[196:199], v182 offset:3072
	ds_read_b128 v[200:203], v182 offset:4096
	ds_read_b128 v[204:207], v182 offset:5120
	ds_read_b128 v[208:211], v182 offset:6144
	ds_read_b128 v[212:215], v182 offset:7168
	s_waitcnt vmcnt(8)
	s_waitcnt lgkmcnt(0)
	s_barrier
	s_waitcnt lgkmcnt(0)
	v_mfma_f32_16x16x32_bf16 v[124:127], v[128:131], v[184:187], v[124:127]
	v_mfma_f32_16x16x32_bf16 v[124:127], v[132:135], v[188:191], v[124:127]
	v_mfma_f32_16x16x32_bf16 v[120:123], v[140:143], v[188:191], v[120:123]
	v_mfma_f32_16x16x32_bf16 v[120:123], v[136:139], v[184:187], v[120:123]
	v_mfma_f32_16x16x32_bf16 v[116:119], v[144:147], v[184:187], v[116:119]
	v_mfma_f32_16x16x32_bf16 v[116:119], v[148:151], v[188:191], v[116:119]
	v_mfma_f32_16x16x32_bf16 v[112:115], v[174:177], v[188:191], v[112:115]
	v_mfma_f32_16x16x32_bf16 v[112:115], v[170:173], v[184:187], v[112:115]
	v_mfma_f32_16x16x32_bf16 v[96:99], v[170:173], v[192:195], v[96:99]
	v_mfma_f32_16x16x32_bf16 v[96:99], v[174:177], v[196:199], v[96:99]
	v_mfma_f32_16x16x32_bf16 v[100:103], v[148:151], v[196:199], v[100:103]
	v_mfma_f32_16x16x32_bf16 v[100:103], v[144:147], v[192:195], v[100:103]
	v_mfma_f32_16x16x32_bf16 v[104:107], v[136:139], v[192:195], v[104:107]
	v_mfma_f32_16x16x32_bf16 v[104:107], v[140:143], v[196:199], v[104:107]
	v_mfma_f32_16x16x32_bf16 v[108:111], v[132:135], v[196:199], v[108:111]
	v_mfma_f32_16x16x32_bf16 v[108:111], v[128:131], v[192:195], v[108:111]
	v_mfma_f32_16x16x32_bf16 v[92:95], v[128:131], v[200:203], v[92:95]
	v_mfma_f32_16x16x32_bf16 v[92:95], v[132:135], v[204:207], v[92:95]
	v_mfma_f32_16x16x32_bf16 v[88:91], v[140:143], v[204:207], v[88:91]
	v_mfma_f32_16x16x32_bf16 v[88:91], v[136:139], v[200:203], v[88:91]
	v_mfma_f32_16x16x32_bf16 v[84:87], v[144:147], v[200:203], v[84:87]
	v_mfma_f32_16x16x32_bf16 v[84:87], v[148:151], v[204:207], v[84:87]
	v_mfma_f32_16x16x32_bf16 v[80:83], v[174:177], v[204:207], v[80:83]
	v_mfma_f32_16x16x32_bf16 v[80:83], v[170:173], v[200:203], v[80:83]
	v_mfma_f32_16x16x32_bf16 v[64:67], v[170:173], v[208:211], v[64:67]
	v_mfma_f32_16x16x32_bf16 v[64:67], v[174:177], v[212:215], v[64:67]
	v_mfma_f32_16x16x32_bf16 v[68:71], v[148:151], v[212:215], v[68:71]
	v_mfma_f32_16x16x32_bf16 v[68:71], v[144:147], v[208:211], v[68:71]
	v_mfma_f32_16x16x32_bf16 v[72:75], v[136:139], v[208:211], v[72:75]
	v_mfma_f32_16x16x32_bf16 v[72:75], v[140:143], v[212:215], v[72:75]
	v_mfma_f32_16x16x32_bf16 v[76:79], v[132:135], v[212:215], v[76:79]
	v_mfma_f32_16x16x32_bf16 v[76:79], v[128:131], v[208:211], v[76:79]
	s_barrier
	s_add_i32 s54, s50, s39
	v_lshl_add_u64 v[216:217], s[26:27], 0, v[154:155]
	s_mov_b32 m0, s54
	v_lshl_add_u64 v[218:219], s[26:27], 0, v[158:159]
	global_load_lds_dwordx4 v[216:217], off
	s_add_i32 m0, s54, 0x2000
	s_add_u32 s54, s26, 0x100000
	s_addc_u32 s55, s27, 0
	s_add_i32 s56, s51, s39
	global_load_lds_dwordx4 v[218:219], off
	v_lshl_add_u64 v[184:185], s[54:55], 0, v[154:155]
	s_mov_b32 m0, s56
	v_lshl_add_u64 v[220:221], s[28:29], 0, v[152:153]
	global_load_lds_dwordx4 v[184:185], off
	v_lshl_add_u64 v[184:185], s[54:55], 0, v[158:159]
	s_add_i32 m0, s56, 0x2000
	v_lshl_add_u64 v[222:223], s[28:29], 0, v[156:157]
	global_load_lds_dwordx4 v[184:185], off
	s_mov_b32 m0, s40
	s_nop 0
	global_load_lds_dwordx4 v[220:221], off
	s_mov_b32 m0, s41
	s_nop 0
	global_load_lds_dwordx4 v[222:223], off
	ds_read_b128 v[184:187], v182 offset:16384
	ds_read_b128 v[188:191], v182 offset:17408
	ds_read_b128 v[192:195], v182 offset:18432
	ds_read_b128 v[196:199], v182 offset:19456
	ds_read_b128 v[200:203], v182 offset:20480
	ds_read_b128 v[204:207], v182 offset:21504
	ds_read_b128 v[208:211], v182 offset:22528
	ds_read_b128 v[212:215], v182 offset:23552
	s_waitcnt vmcnt(8)
	s_waitcnt lgkmcnt(0)
	s_barrier
	s_waitcnt lgkmcnt(0)
	v_mfma_f32_16x16x32_bf16 v[60:63], v[128:131], v[184:187], v[60:63]
	v_mfma_f32_16x16x32_bf16 v[60:63], v[132:135], v[188:191], v[60:63]
	v_mfma_f32_16x16x32_bf16 v[56:59], v[140:143], v[188:191], v[56:59]
	v_mfma_f32_16x16x32_bf16 v[56:59], v[136:139], v[184:187], v[56:59]
	v_mfma_f32_16x16x32_bf16 v[52:55], v[144:147], v[184:187], v[52:55]
	v_mfma_f32_16x16x32_bf16 v[52:55], v[148:151], v[188:191], v[52:55]
	v_mfma_f32_16x16x32_bf16 v[48:51], v[174:177], v[188:191], v[48:51]
	v_mfma_f32_16x16x32_bf16 v[48:51], v[170:173], v[184:187], v[48:51]
	v_mfma_f32_16x16x32_bf16 v[32:35], v[170:173], v[192:195], v[32:35]
	v_mfma_f32_16x16x32_bf16 v[32:35], v[174:177], v[196:199], v[32:35]
	v_mfma_f32_16x16x32_bf16 v[36:39], v[148:151], v[196:199], v[36:39]
	v_mfma_f32_16x16x32_bf16 v[36:39], v[144:147], v[192:195], v[36:39]
	v_mfma_f32_16x16x32_bf16 v[40:43], v[136:139], v[192:195], v[40:43]
	v_mfma_f32_16x16x32_bf16 v[40:43], v[140:143], v[196:199], v[40:43]
	v_mfma_f32_16x16x32_bf16 v[44:47], v[132:135], v[196:199], v[44:47]
	v_mfma_f32_16x16x32_bf16 v[44:47], v[128:131], v[192:195], v[44:47]
	v_mfma_f32_16x16x32_bf16 v[28:31], v[128:131], v[200:203], v[28:31]
	v_mfma_f32_16x16x32_bf16 v[28:31], v[132:135], v[204:207], v[28:31]
	v_mfma_f32_16x16x32_bf16 v[24:27], v[140:143], v[204:207], v[24:27]
	v_mfma_f32_16x16x32_bf16 v[24:27], v[136:139], v[200:203], v[24:27]
	v_mfma_f32_16x16x32_bf16 v[20:23], v[144:147], v[200:203], v[20:23]
	v_mfma_f32_16x16x32_bf16 v[20:23], v[148:151], v[204:207], v[20:23]
	v_mfma_f32_16x16x32_bf16 v[16:19], v[174:177], v[204:207], v[16:19]
	v_mfma_f32_16x16x32_bf16 v[16:19], v[170:173], v[200:203], v[16:19]
	v_mfma_f32_16x16x32_bf16 v[0:3], v[170:173], v[208:211], v[0:3]
	v_mfma_f32_16x16x32_bf16 v[0:3], v[174:177], v[212:215], v[0:3]
	v_mfma_f32_16x16x32_bf16 v[4:7], v[148:151], v[212:215], v[4:7]
	v_mfma_f32_16x16x32_bf16 v[4:7], v[144:147], v[208:211], v[4:7]
	v_mfma_f32_16x16x32_bf16 v[8:11], v[136:139], v[208:211], v[8:11]
	v_mfma_f32_16x16x32_bf16 v[8:11], v[140:143], v[212:215], v[8:11]
	v_mfma_f32_16x16x32_bf16 v[12:15], v[132:135], v[212:215], v[12:15]
	v_mfma_f32_16x16x32_bf16 v[12:15], v[128:131], v[208:211], v[12:15]
	s_barrier
	s_add_i32 s54, 0, 0x18000
	s_add_i32 s55, 0, 0x1c000
	v_add_u32_e32 v140, s54, v178
	v_add_u32_e32 v174, s55, v178
	ds_read_b128 v[128:131], v140
	ds_read_b128 v[132:135], v140 offset:1024
	ds_read_b128 v[136:139], v140 offset:2048
	ds_read_b128 v[140:143], v140 offset:3072
	ds_read_b128 v[144:147], v174
	ds_read_b128 v[148:151], v174 offset:1024
	ds_read_b128 v[170:173], v174 offset:2048
	ds_read_b128 v[174:177], v174 offset:3072
	s_add_u32 s28, s28, 0x40000
	s_addc_u32 s29, s29, 0
	s_mov_b32 m0, s42
	v_lshl_add_u64 v[184:185], s[28:29], 0, v[152:153]
	global_load_lds_dwordx4 v[184:185], off
	v_lshl_add_u64 v[184:185], s[28:29], 0, v[156:157]
	s_mov_b32 m0, s43
	s_nop 0
	global_load_lds_dwordx4 v[184:185], off
	ds_read_b128 v[184:187], v182 offset:32768
	ds_read_b128 v[188:191], v182 offset:33792
	ds_read_b128 v[192:195], v182 offset:34816
	ds_read_b128 v[196:199], v182 offset:35840
	ds_read_b128 v[200:203], v182 offset:36864
	ds_read_b128 v[204:207], v182 offset:37888
	ds_read_b128 v[208:211], v182 offset:38912
	ds_read_b128 v[212:215], v182 offset:39936
	s_waitcnt vmcnt(8)
	s_waitcnt lgkmcnt(0)
	s_barrier
	s_waitcnt lgkmcnt(0)
	v_mfma_f32_16x16x32_bf16 v[124:127], v[128:131], v[184:187], v[124:127]
	v_mfma_f32_16x16x32_bf16 v[124:127], v[132:135], v[188:191], v[124:127]
	v_mfma_f32_16x16x32_bf16 v[120:123], v[140:143], v[188:191], v[120:123]
	v_mfma_f32_16x16x32_bf16 v[120:123], v[136:139], v[184:187], v[120:123]
	v_mfma_f32_16x16x32_bf16 v[116:119], v[144:147], v[184:187], v[116:119]
	v_mfma_f32_16x16x32_bf16 v[116:119], v[148:151], v[188:191], v[116:119]
	v_mfma_f32_16x16x32_bf16 v[112:115], v[174:177], v[188:191], v[112:115]
	v_mfma_f32_16x16x32_bf16 v[112:115], v[170:173], v[184:187], v[112:115]
	v_mfma_f32_16x16x32_bf16 v[96:99], v[170:173], v[192:195], v[96:99]
	v_mfma_f32_16x16x32_bf16 v[96:99], v[174:177], v[196:199], v[96:99]
	v_mfma_f32_16x16x32_bf16 v[100:103], v[148:151], v[196:199], v[100:103]
	v_mfma_f32_16x16x32_bf16 v[100:103], v[144:147], v[192:195], v[100:103]
	v_mfma_f32_16x16x32_bf16 v[104:107], v[136:139], v[192:195], v[104:107]
	v_mfma_f32_16x16x32_bf16 v[104:107], v[140:143], v[196:199], v[104:107]
	v_mfma_f32_16x16x32_bf16 v[108:111], v[132:135], v[196:199], v[108:111]
	v_mfma_f32_16x16x32_bf16 v[108:111], v[128:131], v[192:195], v[108:111]
	v_mfma_f32_16x16x32_bf16 v[92:95], v[128:131], v[200:203], v[92:95]
	v_mfma_f32_16x16x32_bf16 v[92:95], v[132:135], v[204:207], v[92:95]
	v_mfma_f32_16x16x32_bf16 v[88:91], v[140:143], v[204:207], v[88:91]
	v_mfma_f32_16x16x32_bf16 v[88:91], v[136:139], v[200:203], v[88:91]
	v_mfma_f32_16x16x32_bf16 v[84:87], v[144:147], v[200:203], v[84:87]
	v_mfma_f32_16x16x32_bf16 v[84:87], v[148:151], v[204:207], v[84:87]
	v_mfma_f32_16x16x32_bf16 v[80:83], v[174:177], v[204:207], v[80:83]
	v_mfma_f32_16x16x32_bf16 v[80:83], v[170:173], v[200:203], v[80:83]
	v_mfma_f32_16x16x32_bf16 v[64:67], v[170:173], v[208:211], v[64:67]
	v_mfma_f32_16x16x32_bf16 v[64:67], v[174:177], v[212:215], v[64:67]
	v_mfma_f32_16x16x32_bf16 v[68:71], v[148:151], v[212:215], v[68:71]
	v_mfma_f32_16x16x32_bf16 v[68:71], v[144:147], v[208:211], v[68:71]
	v_mfma_f32_16x16x32_bf16 v[72:75], v[136:139], v[208:211], v[72:75]
	v_mfma_f32_16x16x32_bf16 v[72:75], v[140:143], v[212:215], v[72:75]
	v_mfma_f32_16x16x32_bf16 v[76:79], v[132:135], v[212:215], v[76:79]
	v_mfma_f32_16x16x32_bf16 v[76:79], v[128:131], v[208:211], v[76:79]
	s_barrier
	s_add_i32 s28, s54, s39
	v_lshl_add_u64 v[184:185], v[216:217], 0, s[14:15]
	s_mov_b32 m0, s28
	s_nop 0
	global_load_lds_dwordx4 v[184:185], off
	s_add_i32 m0, s28, 0x2000
	s_add_u32 s26, s26, 0x100080
	v_lshl_add_u64 v[184:185], v[218:219], 0, s[14:15]
	s_addc_u32 s27, s27, 0
	s_add_i32 s28, s55, s39
	global_load_lds_dwordx4 v[184:185], off
	v_lshl_add_u64 v[184:185], s[26:27], 0, v[154:155]
	s_mov_b32 m0, s28
	s_nop 0
	global_load_lds_dwordx4 v[184:185], off
	v_lshl_add_u64 v[184:185], s[26:27], 0, v[158:159]
	s_add_i32 m0, s28, 0x2000
	s_nop 0
	global_load_lds_dwordx4 v[184:185], off
	v_lshl_add_u64 v[184:185], v[220:221], 0, s[14:15]
	s_mov_b32 m0, s45
	s_nop 0
	global_load_lds_dwordx4 v[184:185], off
	v_lshl_add_u64 v[184:185], v[222:223], 0, s[14:15]
	s_mov_b32 m0, s46
	s_nop 0
	global_load_lds_dwordx4 v[184:185], off
	ds_read_b128 v[184:187], v182 offset:49152
	ds_read_b128 v[188:191], v182 offset:50176
	ds_read_b128 v[192:195], v182 offset:51200
	ds_read_b128 v[196:199], v182 offset:52224
	ds_read_b128 v[200:203], v182 offset:53248
	ds_read_b128 v[204:207], v182 offset:54272
	ds_read_b128 v[208:211], v182 offset:55296
	ds_read_b128 v[212:215], v182 offset:56320
	s_waitcnt vmcnt(8)
	s_waitcnt lgkmcnt(0)
	s_barrier
	s_waitcnt lgkmcnt(0)
	v_mfma_f32_16x16x32_bf16 v[60:63], v[128:131], v[184:187], v[60:63]
	v_mfma_f32_16x16x32_bf16 v[60:63], v[132:135], v[188:191], v[60:63]
	v_mfma_f32_16x16x32_bf16 v[56:59], v[140:143], v[188:191], v[56:59]
	v_mfma_f32_16x16x32_bf16 v[56:59], v[136:139], v[184:187], v[56:59]
	v_mfma_f32_16x16x32_bf16 v[52:55], v[144:147], v[184:187], v[52:55]
	v_mfma_f32_16x16x32_bf16 v[52:55], v[148:151], v[188:191], v[52:55]
	v_mfma_f32_16x16x32_bf16 v[48:51], v[174:177], v[188:191], v[48:51]
	v_mfma_f32_16x16x32_bf16 v[48:51], v[170:173], v[184:187], v[48:51]
	v_mfma_f32_16x16x32_bf16 v[32:35], v[170:173], v[192:195], v[32:35]
	v_mfma_f32_16x16x32_bf16 v[32:35], v[174:177], v[196:199], v[32:35]
	v_mfma_f32_16x16x32_bf16 v[36:39], v[148:151], v[196:199], v[36:39]
	v_mfma_f32_16x16x32_bf16 v[36:39], v[144:147], v[192:195], v[36:39]
	v_mfma_f32_16x16x32_bf16 v[40:43], v[136:139], v[192:195], v[40:43]
	v_mfma_f32_16x16x32_bf16 v[40:43], v[140:143], v[196:199], v[40:43]
	v_mfma_f32_16x16x32_bf16 v[44:47], v[132:135], v[196:199], v[44:47]
	v_mfma_f32_16x16x32_bf16 v[44:47], v[128:131], v[192:195], v[44:47]
	v_mfma_f32_16x16x32_bf16 v[28:31], v[128:131], v[200:203], v[28:31]
	v_mfma_f32_16x16x32_bf16 v[28:31], v[132:135], v[204:207], v[28:31]
	v_mfma_f32_16x16x32_bf16 v[24:27], v[140:143], v[204:207], v[24:27]
	v_mfma_f32_16x16x32_bf16 v[24:27], v[136:139], v[200:203], v[24:27]
	v_mfma_f32_16x16x32_bf16 v[20:23], v[144:147], v[200:203], v[20:23]
	v_mfma_f32_16x16x32_bf16 v[20:23], v[148:151], v[204:207], v[20:23]
	v_mfma_f32_16x16x32_bf16 v[16:19], v[174:177], v[204:207], v[16:19]
	v_mfma_f32_16x16x32_bf16 v[16:19], v[170:173], v[200:203], v[16:19]
	v_mfma_f32_16x16x32_bf16 v[0:3], v[170:173], v[208:211], v[0:3]
	v_mfma_f32_16x16x32_bf16 v[0:3], v[174:177], v[212:215], v[0:3]
	v_mfma_f32_16x16x32_bf16 v[4:7], v[148:151], v[212:215], v[4:7]
	v_mfma_f32_16x16x32_bf16 v[4:7], v[144:147], v[208:211], v[4:7]
	v_mfma_f32_16x16x32_bf16 v[8:11], v[136:139], v[208:211], v[8:11]
	v_mfma_f32_16x16x32_bf16 v[8:11], v[140:143], v[212:215], v[8:11]
	v_mfma_f32_16x16x32_bf16 v[12:15], v[132:135], v[212:215], v[12:15]
	v_mfma_f32_16x16x32_bf16 v[12:15], v[128:131], v[208:211], v[12:15]
	s_barrier
	s_add_i32 s35, s35, 2
	s_add_u32 s24, s24, 0x100
	s_addc_u32 s25, s25, 0
	s_add_u32 s31, s31, 0x100
	s_addc_u32 s34, s34, 0
	s_cmp_gt_u32 s35, 13
	s_cbranch_scc0 .LBB0_1435
	s_and_b64 vcc, exec, s[8:9]
	s_cbranch_vccz .LBB0_1438
	s_barrier

.LBB0_1543:
	ds_read_b128 v[128:131], v167
	ds_read_b128 v[154:157], v167 offset:1024
	ds_read_b128 v[172:175], v167 offset:2048
	ds_read_b128 v[176:179], v167 offset:3072
	ds_read_b128 v[180:183], v168
	ds_read_b128 v[184:187], v168 offset:1024
	ds_read_b128 v[188:191], v168 offset:2048
	ds_read_b128 v[192:195], v168 offset:3072
	s_add_u32 s22, s20, 0x1000
	s_addc_u32 s23, s21, 0
	s_cmp_eq_u32 s54, 60
	s_cselect_b32 s27, s13, s23
	s_cselect_b32 s26, s50, s22
	s_cselect_b32 s25, s11, s53
	s_cselect_b32 s24, s51, s52
	v_lshl_add_u64 v[160:161], s[20:21], 0, v[144:145]
	s_add_i32 m0, s19, 0xc000
	s_nop 0
	global_load_lds_dwordx4 v[160:161], off
	v_lshl_add_u64 v[160:161], s[20:21], 0, v[146:147]
	s_add_i32 m0, s19, 0xe000
	s_nop 0
	global_load_lds_dwordx4 v[160:161], off
	ds_read_b128 v[196:199], v169
	ds_read_b128 v[200:203], v169 offset:1024
	ds_read_b128 v[204:207], v169 offset:2048
	ds_read_b128 v[208:211], v169 offset:3072
	ds_read_b128 v[212:215], v169 offset:4096
	ds_read_b128 v[216:219], v169 offset:5120
	ds_read_b128 v[220:223], v169 offset:6144
	ds_read_b128 v[224:227], v169 offset:7168
	s_waitcnt vmcnt(8)
	s_waitcnt lgkmcnt(0)
	s_barrier
	s_waitcnt lgkmcnt(0)
	v_mfma_f32_16x16x32_bf16 v[124:127], v[128:131], v[196:199], v[124:127]
	v_mfma_f32_16x16x32_bf16 v[124:127], v[154:157], v[200:203], v[124:127]
	v_mfma_f32_16x16x32_bf16 v[120:123], v[176:179], v[200:203], v[120:123]
	v_mfma_f32_16x16x32_bf16 v[120:123], v[172:175], v[196:199], v[120:123]
	v_mfma_f32_16x16x32_bf16 v[116:119], v[180:183], v[196:199], v[116:119]
	v_mfma_f32_16x16x32_bf16 v[116:119], v[184:187], v[200:203], v[116:119]
	v_mfma_f32_16x16x32_bf16 v[112:115], v[192:195], v[200:203], v[112:115]
	v_mfma_f32_16x16x32_bf16 v[112:115], v[188:191], v[196:199], v[112:115]
	v_mfma_f32_16x16x32_bf16 v[96:99], v[188:191], v[204:207], v[96:99]
	v_mfma_f32_16x16x32_bf16 v[96:99], v[192:195], v[208:211], v[96:99]
	v_mfma_f32_16x16x32_bf16 v[100:103], v[184:187], v[208:211], v[100:103]
	v_mfma_f32_16x16x32_bf16 v[100:103], v[180:183], v[204:207], v[100:103]
	v_mfma_f32_16x16x32_bf16 v[104:107], v[172:175], v[204:207], v[104:107]
	v_mfma_f32_16x16x32_bf16 v[104:107], v[176:179], v[208:211], v[104:107]
	v_mfma_f32_16x16x32_bf16 v[108:111], v[154:157], v[208:211], v[108:111]
	v_mfma_f32_16x16x32_bf16 v[108:111], v[128:131], v[204:207], v[108:111]
	v_mfma_f32_16x16x32_bf16 v[92:95], v[128:131], v[212:215], v[92:95]
	v_mfma_f32_16x16x32_bf16 v[92:95], v[154:157], v[216:219], v[92:95]
	v_mfma_f32_16x16x32_bf16 v[88:91], v[176:179], v[216:219], v[88:91]
	v_mfma_f32_16x16x32_bf16 v[88:91], v[172:175], v[212:215], v[88:91]
	v_mfma_f32_16x16x32_bf16 v[84:87], v[180:183], v[212:215], v[84:87]
	v_mfma_f32_16x16x32_bf16 v[84:87], v[184:187], v[216:219], v[84:87]
	v_mfma_f32_16x16x32_bf16 v[80:83], v[192:195], v[216:219], v[80:83]
	v_mfma_f32_16x16x32_bf16 v[80:83], v[188:191], v[212:215], v[80:83]
	v_mfma_f32_16x16x32_bf16 v[64:67], v[188:191], v[220:223], v[64:67]
	v_mfma_f32_16x16x32_bf16 v[64:67], v[192:195], v[224:227], v[64:67]
	v_mfma_f32_16x16x32_bf16 v[68:71], v[184:187], v[224:227], v[68:71]
	v_mfma_f32_16x16x32_bf16 v[68:71], v[180:183], v[220:223], v[68:71]
	v_mfma_f32_16x16x32_bf16 v[72:75], v[172:175], v[220:223], v[72:75]
	v_mfma_f32_16x16x32_bf16 v[72:75], v[176:179], v[224:227], v[72:75]
	v_mfma_f32_16x16x32_bf16 v[76:79], v[154:157], v[224:227], v[76:79]
	v_mfma_f32_16x16x32_bf16 v[76:79], v[128:131], v[220:223], v[76:79]
	s_barrier
	s_add_i32 s20, s45, s30
	v_lshl_add_u64 v[160:161], s[24:25], 0, v[134:135]
	s_mov_b32 m0, s20
	v_lshl_add_u64 v[164:165], s[24:25], 0, v[138:139]
	global_load_lds_dwordx4 v[160:161], off
	s_add_i32 m0, s20, 0x2000
	s_add_u32 s20, s24, 0x100000
	s_addc_u32 s21, s25, 0
	s_add_i32 s55, s46, s30
	global_load_lds_dwordx4 v[164:165], off
	v_lshl_add_u64 v[196:197], s[20:21], 0, v[134:135]
	s_mov_b32 m0, s55
	v_lshl_add_u64 v[228:229], s[26:27], 0, v[132:133]
	global_load_lds_dwordx4 v[196:197], off
	v_lshl_add_u64 v[196:197], s[20:21], 0, v[138:139]
	s_add_i32 m0, s55, 0x2000
	v_lshl_add_u64 v[230:231], s[26:27], 0, v[136:137]
	global_load_lds_dwordx4 v[196:197], off
	s_mov_b32 m0, s19
	s_nop 0
	global_load_lds_dwordx4 v[228:229], off
	s_mov_b32 m0, s36
	s_nop 0
	global_load_lds_dwordx4 v[230:231], off
	ds_read_b128 v[196:199], v169 offset:16384
	ds_read_b128 v[200:203], v169 offset:17408
	ds_read_b128 v[204:207], v169 offset:18432
	ds_read_b128 v[208:211], v169 offset:19456
	ds_read_b128 v[212:215], v169 offset:20480
	ds_read_b128 v[216:219], v169 offset:21504
	ds_read_b128 v[220:223], v169 offset:22528
	ds_read_b128 v[224:227], v169 offset:23552
	s_waitcnt vmcnt(8)
	s_waitcnt lgkmcnt(0)
	s_barrier
	s_waitcnt lgkmcnt(0)
	v_mfma_f32_16x16x32_bf16 v[60:63], v[128:131], v[196:199], v[60:63]
	v_mfma_f32_16x16x32_bf16 v[60:63], v[154:157], v[200:203], v[60:63]
	v_mfma_f32_16x16x32_bf16 v[56:59], v[176:179], v[200:203], v[56:59]
	v_mfma_f32_16x16x32_bf16 v[56:59], v[172:175], v[196:199], v[56:59]
	v_mfma_f32_16x16x32_bf16 v[52:55], v[180:183], v[196:199], v[52:55]
	v_mfma_f32_16x16x32_bf16 v[52:55], v[184:187], v[200:203], v[52:55]
	v_mfma_f32_16x16x32_bf16 v[48:51], v[192:195], v[200:203], v[48:51]
	v_mfma_f32_16x16x32_bf16 v[48:51], v[188:191], v[196:199], v[48:51]
	v_mfma_f32_16x16x32_bf16 v[32:35], v[188:191], v[204:207], v[32:35]
	v_mfma_f32_16x16x32_bf16 v[32:35], v[192:195], v[208:211], v[32:35]
	v_mfma_f32_16x16x32_bf16 v[36:39], v[184:187], v[208:211], v[36:39]
	v_mfma_f32_16x16x32_bf16 v[36:39], v[180:183], v[204:207], v[36:39]
	v_mfma_f32_16x16x32_bf16 v[40:43], v[172:175], v[204:207], v[40:43]
	v_mfma_f32_16x16x32_bf16 v[40:43], v[176:179], v[208:211], v[40:43]
	v_mfma_f32_16x16x32_bf16 v[44:47], v[154:157], v[208:211], v[44:47]
	v_mfma_f32_16x16x32_bf16 v[44:47], v[128:131], v[204:207], v[44:47]
	v_mfma_f32_16x16x32_bf16 v[28:31], v[128:131], v[212:215], v[28:31]
	v_mfma_f32_16x16x32_bf16 v[28:31], v[154:157], v[216:219], v[28:31]
	v_mfma_f32_16x16x32_bf16 v[24:27], v[176:179], v[216:219], v[24:27]
	v_mfma_f32_16x16x32_bf16 v[24:27], v[172:175], v[212:215], v[24:27]
	v_mfma_f32_16x16x32_bf16 v[20:23], v[180:183], v[212:215], v[20:23]
	v_mfma_f32_16x16x32_bf16 v[20:23], v[184:187], v[216:219], v[20:23]
	v_mfma_f32_16x16x32_bf16 v[16:19], v[192:195], v[216:219], v[16:19]
	v_mfma_f32_16x16x32_bf16 v[16:19], v[188:191], v[212:215], v[16:19]
	v_mfma_f32_16x16x32_bf16 v[0:3], v[188:191], v[220:223], v[0:3]
	v_mfma_f32_16x16x32_bf16 v[0:3], v[192:195], v[224:227], v[0:3]
	v_mfma_f32_16x16x32_bf16 v[4:7], v[184:187], v[224:227], v[4:7]
	v_mfma_f32_16x16x32_bf16 v[4:7], v[180:183], v[220:223], v[4:7]
	v_mfma_f32_16x16x32_bf16 v[8:11], v[172:175], v[220:223], v[8:11]
	v_mfma_f32_16x16x32_bf16 v[8:11], v[176:179], v[224:227], v[8:11]
	v_mfma_f32_16x16x32_bf16 v[12:15], v[154:157], v[224:227], v[12:15]
	v_mfma_f32_16x16x32_bf16 v[12:15], v[128:131], v[220:223], v[12:15]
	s_barrier
	s_add_i32 s55, 0, 0x18000
	v_add_u32_e32 v153, s55, v159
	s_add_i32 s56, 0, 0x1c000
	ds_read_b128 v[128:131], v153
	ds_read_b128 v[154:157], v153 offset:1024
	ds_read_b128 v[172:175], v153 offset:2048
	ds_read_b128 v[176:179], v153 offset:3072
	v_add_u32_e32 v153, s56, v159
	ds_read_b128 v[180:183], v153
	ds_read_b128 v[184:187], v153 offset:1024
	ds_read_b128 v[188:191], v153 offset:2048
	ds_read_b128 v[192:195], v153 offset:3072
	s_add_u32 s20, s26, 0x100000
	s_addc_u32 s21, s27, 0
	s_mov_b32 m0, s37
	v_lshl_add_u64 v[196:197], s[20:21], 0, v[132:133]
	global_load_lds_dwordx4 v[196:197], off
	v_lshl_add_u64 v[196:197], s[20:21], 0, v[136:137]
	s_mov_b32 m0, s38
	s_nop 0
	global_load_lds_dwordx4 v[196:197], off
	ds_read_b128 v[196:199], v169 offset:32768
	ds_read_b128 v[200:203], v169 offset:33792
	ds_read_b128 v[204:207], v169 offset:34816
	ds_read_b128 v[208:211], v169 offset:35840
	ds_read_b128 v[212:215], v169 offset:36864
	ds_read_b128 v[216:219], v169 offset:37888
	ds_read_b128 v[220:223], v169 offset:38912
	ds_read_b128 v[224:227], v169 offset:39936
	s_waitcnt vmcnt(8)
	s_waitcnt lgkmcnt(0)
	s_barrier
	s_waitcnt lgkmcnt(0)
	v_mfma_f32_16x16x32_bf16 v[124:127], v[128:131], v[196:199], v[124:127]
	v_mfma_f32_16x16x32_bf16 v[124:127], v[154:157], v[200:203], v[124:127]
	v_mfma_f32_16x16x32_bf16 v[120:123], v[176:179], v[200:203], v[120:123]
	v_mfma_f32_16x16x32_bf16 v[120:123], v[172:175], v[196:199], v[120:123]
	v_mfma_f32_16x16x32_bf16 v[116:119], v[180:183], v[196:199], v[116:119]
	v_mfma_f32_16x16x32_bf16 v[116:119], v[184:187], v[200:203], v[116:119]
	v_mfma_f32_16x16x32_bf16 v[112:115], v[192:195], v[200:203], v[112:115]
	v_mfma_f32_16x16x32_bf16 v[112:115], v[188:191], v[196:199], v[112:115]
	v_mfma_f32_16x16x32_bf16 v[96:99], v[188:191], v[204:207], v[96:99]
	v_mfma_f32_16x16x32_bf16 v[96:99], v[192:195], v[208:211], v[96:99]
	v_mfma_f32_16x16x32_bf16 v[100:103], v[184:187], v[208:211], v[100:103]
	v_mfma_f32_16x16x32_bf16 v[100:103], v[180:183], v[204:207], v[100:103]
	v_mfma_f32_16x16x32_bf16 v[104:107], v[172:175], v[204:207], v[104:107]
	v_mfma_f32_16x16x32_bf16 v[104:107], v[176:179], v[208:211], v[104:107]
	v_mfma_f32_16x16x32_bf16 v[108:111], v[154:157], v[208:211], v[108:111]
	v_mfma_f32_16x16x32_bf16 v[108:111], v[128:131], v[204:207], v[108:111]
	v_mfma_f32_16x16x32_bf16 v[92:95], v[128:131], v[212:215], v[92:95]
	v_mfma_f32_16x16x32_bf16 v[92:95], v[154:157], v[216:219], v[92:95]
	v_mfma_f32_16x16x32_bf16 v[88:91], v[176:179], v[216:219], v[88:91]
	v_mfma_f32_16x16x32_bf16 v[88:91], v[172:175], v[212:215], v[88:91]
	v_mfma_f32_16x16x32_bf16 v[84:87], v[180:183], v[212:215], v[84:87]
	v_mfma_f32_16x16x32_bf16 v[84:87], v[184:187], v[216:219], v[84:87]
	v_mfma_f32_16x16x32_bf16 v[80:83], v[192:195], v[216:219], v[80:83]
	v_mfma_f32_16x16x32_bf16 v[80:83], v[188:191], v[212:215], v[80:83]
	v_mfma_f32_16x16x32_bf16 v[64:67], v[188:191], v[220:223], v[64:67]
	v_mfma_f32_16x16x32_bf16 v[64:67], v[192:195], v[224:227], v[64:67]
	v_mfma_f32_16x16x32_bf16 v[68:71], v[184:187], v[224:227], v[68:71]
	v_mfma_f32_16x16x32_bf16 v[68:71], v[180:183], v[220:223], v[68:71]
	v_mfma_f32_16x16x32_bf16 v[72:75], v[172:175], v[220:223], v[72:75]
	v_mfma_f32_16x16x32_bf16 v[72:75], v[176:179], v[224:227], v[72:75]
	v_mfma_f32_16x16x32_bf16 v[76:79], v[154:157], v[224:227], v[76:79]
	v_mfma_f32_16x16x32_bf16 v[76:79], v[128:131], v[220:223], v[76:79]
	s_barrier
	s_add_i32 s20, s55, s30
	v_lshl_add_u64 v[160:161], v[160:161], 0, s[8:9]
	s_mov_b32 m0, s20
	s_nop 0
	global_load_lds_dwordx4 v[160:161], off
	s_add_i32 m0, s20, 0x2000
	s_add_u32 s20, s24, 0x100800
	v_lshl_add_u64 v[160:161], v[164:165], 0, s[8:9]
	s_addc_u32 s21, s25, 0
	s_add_i32 s24, s56, s30
	global_load_lds_dwordx4 v[160:161], off
	v_lshl_add_u64 v[160:161], s[20:21], 0, v[134:135]
	s_mov_b32 m0, s24
	s_nop 0
	global_load_lds_dwordx4 v[160:161], off
	v_lshl_add_u64 v[160:161], s[20:21], 0, v[138:139]
	s_add_i32 m0, s24, 0x2000
	s_nop 0
	global_load_lds_dwordx4 v[160:161], off
	v_lshl_add_u64 v[160:161], v[228:229], 0, s[8:9]
	s_mov_b32 m0, s41
	s_nop 0
	global_load_lds_dwordx4 v[160:161], off
	v_lshl_add_u64 v[160:161], v[230:231], 0, s[8:9]
	s_mov_b32 m0, s42
	s_nop 0
	global_load_lds_dwordx4 v[160:161], off
	ds_read_b128 v[196:199], v169 offset:49152
	ds_read_b128 v[200:203], v169 offset:50176
	ds_read_b128 v[204:207], v169 offset:51200
	ds_read_b128 v[208:211], v169 offset:52224
	ds_read_b128 v[212:215], v169 offset:53248
	ds_read_b128 v[216:219], v169 offset:54272
	ds_read_b128 v[220:223], v169 offset:55296
	ds_read_b128 v[224:227], v169 offset:56320
	s_waitcnt vmcnt(8)
	s_waitcnt lgkmcnt(0)
	s_barrier
	s_waitcnt lgkmcnt(0)
	v_mfma_f32_16x16x32_bf16 v[60:63], v[128:131], v[196:199], v[60:63]
	v_mfma_f32_16x16x32_bf16 v[60:63], v[154:157], v[200:203], v[60:63]
	v_mfma_f32_16x16x32_bf16 v[56:59], v[176:179], v[200:203], v[56:59]
	v_mfma_f32_16x16x32_bf16 v[56:59], v[172:175], v[196:199], v[56:59]
	v_mfma_f32_16x16x32_bf16 v[52:55], v[180:183], v[196:199], v[52:55]
	v_mfma_f32_16x16x32_bf16 v[52:55], v[184:187], v[200:203], v[52:55]
	v_mfma_f32_16x16x32_bf16 v[48:51], v[192:195], v[200:203], v[48:51]
	v_mfma_f32_16x16x32_bf16 v[48:51], v[188:191], v[196:199], v[48:51]
	v_mfma_f32_16x16x32_bf16 v[32:35], v[188:191], v[204:207], v[32:35]
	v_mfma_f32_16x16x32_bf16 v[32:35], v[192:195], v[208:211], v[32:35]
	v_mfma_f32_16x16x32_bf16 v[36:39], v[184:187], v[208:211], v[36:39]
	v_mfma_f32_16x16x32_bf16 v[36:39], v[180:183], v[204:207], v[36:39]
	v_mfma_f32_16x16x32_bf16 v[40:43], v[172:175], v[204:207], v[40:43]
	v_mfma_f32_16x16x32_bf16 v[40:43], v[176:179], v[208:211], v[40:43]
	v_mfma_f32_16x16x32_bf16 v[44:47], v[154:157], v[208:211], v[44:47]
	v_mfma_f32_16x16x32_bf16 v[44:47], v[128:131], v[204:207], v[44:47]
	v_mfma_f32_16x16x32_bf16 v[28:31], v[128:131], v[212:215], v[28:31]
	v_mfma_f32_16x16x32_bf16 v[28:31], v[154:157], v[216:219], v[28:31]
	v_mfma_f32_16x16x32_bf16 v[24:27], v[176:179], v[216:219], v[24:27]
	v_mfma_f32_16x16x32_bf16 v[24:27], v[172:175], v[212:215], v[24:27]
	v_mfma_f32_16x16x32_bf16 v[20:23], v[180:183], v[212:215], v[20:23]
	v_mfma_f32_16x16x32_bf16 v[20:23], v[184:187], v[216:219], v[20:23]
	v_mfma_f32_16x16x32_bf16 v[16:19], v[192:195], v[216:219], v[16:19]
	v_mfma_f32_16x16x32_bf16 v[16:19], v[188:191], v[212:215], v[16:19]
	v_mfma_f32_16x16x32_bf16 v[0:3], v[188:191], v[220:223], v[0:3]
	v_mfma_f32_16x16x32_bf16 v[0:3], v[192:195], v[224:227], v[0:3]
	v_mfma_f32_16x16x32_bf16 v[4:7], v[184:187], v[224:227], v[4:7]
	v_mfma_f32_16x16x32_bf16 v[4:7], v[180:183], v[220:223], v[4:7]
	v_mfma_f32_16x16x32_bf16 v[8:11], v[172:175], v[220:223], v[8:11]
	v_mfma_f32_16x16x32_bf16 v[8:11], v[176:179], v[224:227], v[8:11]
	v_mfma_f32_16x16x32_bf16 v[12:15], v[154:157], v[224:227], v[12:15]
	v_mfma_f32_16x16x32_bf16 v[12:15], v[128:131], v[220:223], v[12:15]
	s_barrier
	s_add_i32 s54, s54, 2
	s_add_u32 s52, s52, 0x1000
	s_addc_u32 s53, s53, 0
	s_cmp_gt_u32 s54, 61
	s_mov_b64 s[20:21], s[22:23]
	s_cbranch_scc0 .LBB0_1543
	s_and_b64 vcc, exec, s[4:5]
	s_cbranch_vccz .LBB0_1546
	s_barrier

.LBB0_1625:
	ds_read_b128 v[128:131], v177
	ds_read_b128 v[132:135], v177 offset:1024
	ds_read_b128 v[136:139], v177 offset:2048
	ds_read_b128 v[140:143], v177 offset:3072
	ds_read_b128 v[144:147], v178
	ds_read_b128 v[148:151], v178 offset:1024
	ds_read_b128 v[170:173], v178 offset:2048
	ds_read_b128 v[182:185], v178 offset:3072
	s_add_u32 s24, s22, 0xffc00800
	s_addc_u32 s25, s23, -1
	s_cmpk_eq_i32 s57, 0xfc
	s_cselect_b32 s27, s29, s25
	s_cselect_b32 s26, s53, s24
	s_cselect_b32 s25, s17, s56
	s_cselect_b32 s24, s54, s55
	v_lshl_add_u64 v[186:187], s[22:23], 0, v[162:163]
	s_add_i32 m0, s38, 0xc000
	s_nop 0
	global_load_lds_dwordx4 v[186:187], off
	v_lshl_add_u64 v[186:187], s[22:23], 0, v[164:165]
	s_add_i32 m0, s38, 0xe000
	s_nop 0
	global_load_lds_dwordx4 v[186:187], off
	ds_read_b128 v[186:189], v179
	ds_read_b128 v[190:193], v179 offset:1024
	ds_read_b128 v[194:197], v179 offset:2048
	ds_read_b128 v[198:201], v179 offset:3072
	ds_read_b128 v[202:205], v179 offset:4096
	ds_read_b128 v[206:209], v179 offset:5120
	ds_read_b128 v[210:213], v179 offset:6144
	ds_read_b128 v[214:217], v179 offset:7168
	s_waitcnt vmcnt(8)
	s_waitcnt lgkmcnt(0)
	s_barrier
	s_waitcnt lgkmcnt(0)
	v_mfma_f32_16x16x32_bf16 v[124:127], v[128:131], v[186:189], v[124:127]
	v_mfma_f32_16x16x32_bf16 v[124:127], v[132:135], v[190:193], v[124:127]
	v_mfma_f32_16x16x32_bf16 v[120:123], v[140:143], v[190:193], v[120:123]
	v_mfma_f32_16x16x32_bf16 v[120:123], v[136:139], v[186:189], v[120:123]
	v_mfma_f32_16x16x32_bf16 v[116:119], v[144:147], v[186:189], v[116:119]
	v_mfma_f32_16x16x32_bf16 v[116:119], v[148:151], v[190:193], v[116:119]
	v_mfma_f32_16x16x32_bf16 v[112:115], v[182:185], v[190:193], v[112:115]
	v_mfma_f32_16x16x32_bf16 v[112:115], v[170:173], v[186:189], v[112:115]
	v_mfma_f32_16x16x32_bf16 v[96:99], v[170:173], v[194:197], v[96:99]
	v_mfma_f32_16x16x32_bf16 v[96:99], v[182:185], v[198:201], v[96:99]
	v_mfma_f32_16x16x32_bf16 v[100:103], v[148:151], v[198:201], v[100:103]
	v_mfma_f32_16x16x32_bf16 v[100:103], v[144:147], v[194:197], v[100:103]
	v_mfma_f32_16x16x32_bf16 v[104:107], v[136:139], v[194:197], v[104:107]
	v_mfma_f32_16x16x32_bf16 v[104:107], v[140:143], v[198:201], v[104:107]
	v_mfma_f32_16x16x32_bf16 v[108:111], v[132:135], v[198:201], v[108:111]
	v_mfma_f32_16x16x32_bf16 v[108:111], v[128:131], v[194:197], v[108:111]
	v_mfma_f32_16x16x32_bf16 v[92:95], v[128:131], v[202:205], v[92:95]
	v_mfma_f32_16x16x32_bf16 v[92:95], v[132:135], v[206:209], v[92:95]
	v_mfma_f32_16x16x32_bf16 v[88:91], v[140:143], v[206:209], v[88:91]
	v_mfma_f32_16x16x32_bf16 v[88:91], v[136:139], v[202:205], v[88:91]
	v_mfma_f32_16x16x32_bf16 v[84:87], v[144:147], v[202:205], v[84:87]
	v_mfma_f32_16x16x32_bf16 v[84:87], v[148:151], v[206:209], v[84:87]
	v_mfma_f32_16x16x32_bf16 v[80:83], v[182:185], v[206:209], v[80:83]
	v_mfma_f32_16x16x32_bf16 v[80:83], v[170:173], v[202:205], v[80:83]
	v_mfma_f32_16x16x32_bf16 v[64:67], v[170:173], v[210:213], v[64:67]
	v_mfma_f32_16x16x32_bf16 v[64:67], v[182:185], v[214:217], v[64:67]
	v_mfma_f32_16x16x32_bf16 v[68:71], v[148:151], v[214:217], v[68:71]
	v_mfma_f32_16x16x32_bf16 v[68:71], v[144:147], v[210:213], v[68:71]
	v_mfma_f32_16x16x32_bf16 v[72:75], v[136:139], v[210:213], v[72:75]
	v_mfma_f32_16x16x32_bf16 v[72:75], v[140:143], v[214:217], v[72:75]
	v_mfma_f32_16x16x32_bf16 v[76:79], v[132:135], v[214:217], v[76:79]
	v_mfma_f32_16x16x32_bf16 v[76:79], v[128:131], v[210:213], v[76:79]
	s_barrier
	s_add_i32 s58, s48, s37
	v_lshl_add_u64 v[218:219], s[24:25], 0, v[154:155]
	s_mov_b32 m0, s58
	v_lshl_add_u64 v[220:221], s[24:25], 0, v[158:159]
	global_load_lds_dwordx4 v[218:219], off
	s_add_i32 m0, s58, 0x2000
	s_add_u32 s58, s24, 0x400000
	s_addc_u32 s59, s25, 0
	s_add_i32 s60, s49, s37
	global_load_lds_dwordx4 v[220:221], off
	v_lshl_add_u64 v[186:187], s[58:59], 0, v[154:155]
	s_mov_b32 m0, s60
	v_lshl_add_u64 v[222:223], s[26:27], 0, v[152:153]
	global_load_lds_dwordx4 v[186:187], off
	v_lshl_add_u64 v[186:187], s[58:59], 0, v[158:159]
	s_add_i32 m0, s60, 0x2000
	v_lshl_add_u64 v[224:225], s[26:27], 0, v[156:157]
	global_load_lds_dwordx4 v[186:187], off
	s_mov_b32 m0, s38
	s_nop 0
	global_load_lds_dwordx4 v[222:223], off
	s_mov_b32 m0, s39
	s_nop 0
	global_load_lds_dwordx4 v[224:225], off
	ds_read_b128 v[186:189], v179 offset:16384
	ds_read_b128 v[190:193], v179 offset:17408
	ds_read_b128 v[194:197], v179 offset:18432
	ds_read_b128 v[198:201], v179 offset:19456
	ds_read_b128 v[202:205], v179 offset:20480
	ds_read_b128 v[206:209], v179 offset:21504
	ds_read_b128 v[210:213], v179 offset:22528
	ds_read_b128 v[214:217], v179 offset:23552
	s_waitcnt vmcnt(8)
	s_waitcnt lgkmcnt(0)
	s_barrier
	s_waitcnt lgkmcnt(0)
	v_mfma_f32_16x16x32_bf16 v[60:63], v[128:131], v[186:189], v[60:63]
	v_mfma_f32_16x16x32_bf16 v[60:63], v[132:135], v[190:193], v[60:63]
	v_mfma_f32_16x16x32_bf16 v[56:59], v[140:143], v[190:193], v[56:59]
	v_mfma_f32_16x16x32_bf16 v[56:59], v[136:139], v[186:189], v[56:59]
	v_mfma_f32_16x16x32_bf16 v[52:55], v[144:147], v[186:189], v[52:55]
	v_mfma_f32_16x16x32_bf16 v[52:55], v[148:151], v[190:193], v[52:55]
	v_mfma_f32_16x16x32_bf16 v[48:51], v[182:185], v[190:193], v[48:51]
	v_mfma_f32_16x16x32_bf16 v[48:51], v[170:173], v[186:189], v[48:51]
	v_mfma_f32_16x16x32_bf16 v[32:35], v[170:173], v[194:197], v[32:35]
	v_mfma_f32_16x16x32_bf16 v[32:35], v[182:185], v[198:201], v[32:35]
	v_mfma_f32_16x16x32_bf16 v[36:39], v[148:151], v[198:201], v[36:39]
	v_mfma_f32_16x16x32_bf16 v[36:39], v[144:147], v[194:197], v[36:39]
	v_mfma_f32_16x16x32_bf16 v[40:43], v[136:139], v[194:197], v[40:43]
	v_mfma_f32_16x16x32_bf16 v[40:43], v[140:143], v[198:201], v[40:43]
	v_mfma_f32_16x16x32_bf16 v[44:47], v[132:135], v[198:201], v[44:47]
	v_mfma_f32_16x16x32_bf16 v[44:47], v[128:131], v[194:197], v[44:47]
	v_mfma_f32_16x16x32_bf16 v[28:31], v[128:131], v[202:205], v[28:31]
	v_mfma_f32_16x16x32_bf16 v[28:31], v[132:135], v[206:209], v[28:31]
	v_mfma_f32_16x16x32_bf16 v[24:27], v[140:143], v[206:209], v[24:27]
	v_mfma_f32_16x16x32_bf16 v[24:27], v[136:139], v[202:205], v[24:27]
	v_mfma_f32_16x16x32_bf16 v[20:23], v[144:147], v[202:205], v[20:23]
	v_mfma_f32_16x16x32_bf16 v[20:23], v[148:151], v[206:209], v[20:23]
	v_mfma_f32_16x16x32_bf16 v[16:19], v[182:185], v[206:209], v[16:19]
	v_mfma_f32_16x16x32_bf16 v[16:19], v[170:173], v[202:205], v[16:19]
	v_mfma_f32_16x16x32_bf16 v[0:3], v[170:173], v[210:213], v[0:3]
	v_mfma_f32_16x16x32_bf16 v[0:3], v[182:185], v[214:217], v[0:3]
	v_mfma_f32_16x16x32_bf16 v[4:7], v[148:151], v[214:217], v[4:7]
	v_mfma_f32_16x16x32_bf16 v[4:7], v[144:147], v[210:213], v[4:7]
	v_mfma_f32_16x16x32_bf16 v[8:11], v[136:139], v[210:213], v[8:11]
	v_mfma_f32_16x16x32_bf16 v[8:11], v[140:143], v[214:217], v[8:11]
	v_mfma_f32_16x16x32_bf16 v[12:15], v[132:135], v[214:217], v[12:15]
	v_mfma_f32_16x16x32_bf16 v[12:15], v[128:131], v[210:213], v[12:15]
	s_barrier
	s_add_i32 s58, 0, 0x18000
	s_add_i32 s59, 0, 0x1c000
	v_add_u32_e32 v140, s58, v174
	v_add_u32_e32 v181, s59, v174
	ds_read_b128 v[128:131], v140
	ds_read_b128 v[132:135], v140 offset:1024
	ds_read_b128 v[136:139], v140 offset:2048
	ds_read_b128 v[140:143], v140 offset:3072
	ds_read_b128 v[144:147], v181
	ds_read_b128 v[148:151], v181 offset:1024
	ds_read_b128 v[170:173], v181 offset:2048
	ds_read_b128 v[182:185], v181 offset:3072
	s_add_u32 s26, s26, 0x400000
	s_addc_u32 s27, s27, 0
	s_mov_b32 m0, s40
	v_lshl_add_u64 v[186:187], s[26:27], 0, v[152:153]
	global_load_lds_dwordx4 v[186:187], off
	v_lshl_add_u64 v[186:187], s[26:27], 0, v[156:157]
	s_mov_b32 m0, s41
	s_nop 0
	global_load_lds_dwordx4 v[186:187], off
	ds_read_b128 v[186:189], v179 offset:32768
	ds_read_b128 v[190:193], v179 offset:33792
	ds_read_b128 v[194:197], v179 offset:34816
	ds_read_b128 v[198:201], v179 offset:35840
	ds_read_b128 v[202:205], v179 offset:36864
	ds_read_b128 v[206:209], v179 offset:37888
	ds_read_b128 v[210:213], v179 offset:38912
	ds_read_b128 v[214:217], v179 offset:39936
	s_waitcnt vmcnt(8)
	s_waitcnt lgkmcnt(0)
	s_barrier
	s_waitcnt lgkmcnt(0)
	v_mfma_f32_16x16x32_bf16 v[124:127], v[128:131], v[186:189], v[124:127]
	v_mfma_f32_16x16x32_bf16 v[124:127], v[132:135], v[190:193], v[124:127]
	v_mfma_f32_16x16x32_bf16 v[120:123], v[140:143], v[190:193], v[120:123]
	v_mfma_f32_16x16x32_bf16 v[120:123], v[136:139], v[186:189], v[120:123]
	v_mfma_f32_16x16x32_bf16 v[116:119], v[144:147], v[186:189], v[116:119]
	v_mfma_f32_16x16x32_bf16 v[116:119], v[148:151], v[190:193], v[116:119]
	v_mfma_f32_16x16x32_bf16 v[112:115], v[182:185], v[190:193], v[112:115]
	v_mfma_f32_16x16x32_bf16 v[112:115], v[170:173], v[186:189], v[112:115]
	v_mfma_f32_16x16x32_bf16 v[96:99], v[170:173], v[194:197], v[96:99]
	v_mfma_f32_16x16x32_bf16 v[96:99], v[182:185], v[198:201], v[96:99]
	v_mfma_f32_16x16x32_bf16 v[100:103], v[148:151], v[198:201], v[100:103]
	v_mfma_f32_16x16x32_bf16 v[100:103], v[144:147], v[194:197], v[100:103]
	v_mfma_f32_16x16x32_bf16 v[104:107], v[136:139], v[194:197], v[104:107]
	v_mfma_f32_16x16x32_bf16 v[104:107], v[140:143], v[198:201], v[104:107]
	v_mfma_f32_16x16x32_bf16 v[108:111], v[132:135], v[198:201], v[108:111]
	v_mfma_f32_16x16x32_bf16 v[108:111], v[128:131], v[194:197], v[108:111]
	v_mfma_f32_16x16x32_bf16 v[92:95], v[128:131], v[202:205], v[92:95]
	v_mfma_f32_16x16x32_bf16 v[92:95], v[132:135], v[206:209], v[92:95]
	v_mfma_f32_16x16x32_bf16 v[88:91], v[140:143], v[206:209], v[88:91]
	v_mfma_f32_16x16x32_bf16 v[88:91], v[136:139], v[202:205], v[88:91]
	v_mfma_f32_16x16x32_bf16 v[84:87], v[144:147], v[202:205], v[84:87]
	v_mfma_f32_16x16x32_bf16 v[84:87], v[148:151], v[206:209], v[84:87]
	v_mfma_f32_16x16x32_bf16 v[80:83], v[182:185], v[206:209], v[80:83]
	v_mfma_f32_16x16x32_bf16 v[80:83], v[170:173], v[202:205], v[80:83]
	v_mfma_f32_16x16x32_bf16 v[64:67], v[170:173], v[210:213], v[64:67]
	v_mfma_f32_16x16x32_bf16 v[64:67], v[182:185], v[214:217], v[64:67]
	v_mfma_f32_16x16x32_bf16 v[68:71], v[148:151], v[214:217], v[68:71]
	v_mfma_f32_16x16x32_bf16 v[68:71], v[144:147], v[210:213], v[68:71]
	v_mfma_f32_16x16x32_bf16 v[72:75], v[136:139], v[210:213], v[72:75]
	v_mfma_f32_16x16x32_bf16 v[72:75], v[140:143], v[214:217], v[72:75]
	v_mfma_f32_16x16x32_bf16 v[76:79], v[132:135], v[214:217], v[76:79]
	v_mfma_f32_16x16x32_bf16 v[76:79], v[128:131], v[210:213], v[76:79]
	s_barrier
	s_add_i32 s26, s58, s37
	v_lshl_add_u64 v[186:187], v[218:219], 0, s[14:15]
	s_mov_b32 m0, s26
	s_nop 0
	global_load_lds_dwordx4 v[186:187], off
	s_add_i32 m0, s26, 0x2000
	s_add_u32 s24, s24, 0x400800
	v_lshl_add_u64 v[186:187], v[220:221], 0, s[14:15]
	s_addc_u32 s25, s25, 0
	s_add_i32 s26, s59, s37
	global_load_lds_dwordx4 v[186:187], off
	v_lshl_add_u64 v[186:187], s[24:25], 0, v[154:155]
	s_mov_b32 m0, s26
	s_nop 0
	global_load_lds_dwordx4 v[186:187], off
	v_lshl_add_u64 v[186:187], s[24:25], 0, v[158:159]
	s_add_i32 m0, s26, 0x2000
	s_nop 0
	global_load_lds_dwordx4 v[186:187], off
	v_lshl_add_u64 v[186:187], v[222:223], 0, s[14:15]
	s_mov_b32 m0, s43
	s_nop 0
	global_load_lds_dwordx4 v[186:187], off
	v_lshl_add_u64 v[186:187], v[224:225], 0, s[14:15]
	s_mov_b32 m0, s44
	s_nop 0
	global_load_lds_dwordx4 v[186:187], off
	ds_read_b128 v[186:189], v179 offset:49152
	ds_read_b128 v[190:193], v179 offset:50176
	ds_read_b128 v[194:197], v179 offset:51200
	ds_read_b128 v[198:201], v179 offset:52224
	ds_read_b128 v[202:205], v179 offset:53248
	ds_read_b128 v[206:209], v179 offset:54272
	ds_read_b128 v[210:213], v179 offset:55296
	ds_read_b128 v[214:217], v179 offset:56320
	s_waitcnt vmcnt(8)
	s_waitcnt lgkmcnt(0)
	s_barrier
	s_waitcnt lgkmcnt(0)
	v_mfma_f32_16x16x32_bf16 v[60:63], v[128:131], v[186:189], v[60:63]
	v_mfma_f32_16x16x32_bf16 v[60:63], v[132:135], v[190:193], v[60:63]
	v_mfma_f32_16x16x32_bf16 v[56:59], v[140:143], v[190:193], v[56:59]
	v_mfma_f32_16x16x32_bf16 v[56:59], v[136:139], v[186:189], v[56:59]
	v_mfma_f32_16x16x32_bf16 v[52:55], v[144:147], v[186:189], v[52:55]
	v_mfma_f32_16x16x32_bf16 v[52:55], v[148:151], v[190:193], v[52:55]
	v_mfma_f32_16x16x32_bf16 v[48:51], v[182:185], v[190:193], v[48:51]
	v_mfma_f32_16x16x32_bf16 v[48:51], v[170:173], v[186:189], v[48:51]
	v_mfma_f32_16x16x32_bf16 v[32:35], v[170:173], v[194:197], v[32:35]
	v_mfma_f32_16x16x32_bf16 v[32:35], v[182:185], v[198:201], v[32:35]
	v_mfma_f32_16x16x32_bf16 v[36:39], v[148:151], v[198:201], v[36:39]
	v_mfma_f32_16x16x32_bf16 v[36:39], v[144:147], v[194:197], v[36:39]
	v_mfma_f32_16x16x32_bf16 v[40:43], v[136:139], v[194:197], v[40:43]
	v_mfma_f32_16x16x32_bf16 v[40:43], v[140:143], v[198:201], v[40:43]
	v_mfma_f32_16x16x32_bf16 v[44:47], v[132:135], v[198:201], v[44:47]
	v_mfma_f32_16x16x32_bf16 v[44:47], v[128:131], v[194:197], v[44:47]
	v_mfma_f32_16x16x32_bf16 v[28:31], v[128:131], v[202:205], v[28:31]
	v_mfma_f32_16x16x32_bf16 v[28:31], v[132:135], v[206:209], v[28:31]
	v_mfma_f32_16x16x32_bf16 v[24:27], v[140:143], v[206:209], v[24:27]
	v_mfma_f32_16x16x32_bf16 v[24:27], v[136:139], v[202:205], v[24:27]
	v_mfma_f32_16x16x32_bf16 v[20:23], v[144:147], v[202:205], v[20:23]
	v_mfma_f32_16x16x32_bf16 v[20:23], v[148:151], v[206:209], v[20:23]
	v_mfma_f32_16x16x32_bf16 v[16:19], v[182:185], v[206:209], v[16:19]
	v_mfma_f32_16x16x32_bf16 v[16:19], v[170:173], v[202:205], v[16:19]
	v_mfma_f32_16x16x32_bf16 v[0:3], v[170:173], v[210:213], v[0:3]
	v_mfma_f32_16x16x32_bf16 v[0:3], v[182:185], v[214:217], v[0:3]
	v_mfma_f32_16x16x32_bf16 v[4:7], v[148:151], v[214:217], v[4:7]
	v_mfma_f32_16x16x32_bf16 v[4:7], v[144:147], v[210:213], v[4:7]
	v_mfma_f32_16x16x32_bf16 v[8:11], v[136:139], v[210:213], v[8:11]
	v_mfma_f32_16x16x32_bf16 v[8:11], v[140:143], v[214:217], v[8:11]
	v_mfma_f32_16x16x32_bf16 v[12:15], v[132:135], v[214:217], v[12:15]
	v_mfma_f32_16x16x32_bf16 v[12:15], v[128:131], v[210:213], v[12:15]
	s_barrier
	s_add_i32 s57, s57, 2
	s_add_u32 s22, s22, 0x1000
	s_addc_u32 s23, s23, 0
	s_add_u32 s55, s55, 0x1000
	s_addc_u32 s56, s56, 0
	s_cmpk_gt_u32 s57, 0xfd
	s_cbranch_scc0 .LBB0_1625
	s_and_b64 vcc, exec, s[6:7]
	s_cbranch_vccz .LBB0_1628
	s_barrier
